# PEER v-side (phase 10) rewritten by hand: workgroup owns 32 tokens and sweeps 8 column slices, act formed once per token (not 8x), LDS-staged gate/offset broadcast, permlane/DPP reduction; f32 math, f
# speedup vs baseline: 1.0705x; 1.0705x over previous
; DI unsigned xb_add(unsigned* p, unsigned v) { return __hip_atomic_fetch_add(p, v, __ATOMIC_RELAXED, __HIP_MEMORY_SCOPE_AGENT); }
; DI unsigned xb_xcc_id() { return (unsigned)__builtin_amdgcn_s_getreg((3 << 11) | 20) & 0xFu; }
; __global__ void __launch_bounds__(256, 2) fwd_megakernel(Params p) {
;   __shared__ __attribute__((aligned(256))) char smem_all[SMEM_BYTES];
;   char* smem = smem_all + 256;
;   const int bid = blockIdx.x, nb = gridDim.x;
;   const bool multi = (p.phase_hi - p.phase_lo) > 1;
;   XcdBarrier xb; xb.bar = p.bar; xb.x = 0; xb.st = (volatile unsigned*)smem_all;
;   if (multi) {
;     if (threadIdx.x == 0) { ((volatile unsigned*)smem_all)[0] = 0u; ((volatile unsigned*)smem_all)[1] = 0u; }
;     __syncthreads();
;     xb.x = xb_xcc_id();
;     if (threadIdx.x == 0) (void)xb_add(&p.bar[XB_XCNT(xb.x)], 1u);
;   }
_Z14fwd_megakernel6Params:
	s_mov_b32 s100, s2
	s_load_dwordx16 s[40:55], s[0:1], 0x80
	s_load_dwordx4 s[12:15], s[0:1], 0x138
	s_load_dwordx2 s[8:9], s[0:1], 0x1c0
	s_load_dwordx8 s[16:23], s[0:1], 0x118
	s_load_dword s4, s[0:1], 0x1c8
	s_add_u32 s6, s0, 0x1c8
	s_addc_u32 s7, s1, 0
	s_mov_b32 s10, 0
	s_waitcnt lgkmcnt(0)
	v_writelane_b32 v253, s16, 0
	s_nop 1
	v_writelane_b32 v253, s17, 1
	v_writelane_b32 v253, s18, 2
	v_writelane_b32 v253, s19, 3
	v_writelane_b32 v253, s20, 4
	v_writelane_b32 v253, s21, 5
	v_writelane_b32 v253, s22, 6
	v_writelane_b32 v253, s23, 7
	v_writelane_b32 v253, s4, 8
	s_nop 1
	v_writelane_b32 v253, s5, 9
	v_writelane_b32 v253, s6, 10
	s_nop 1
	v_writelane_b32 v253, s7, 11
	v_writelane_b32 v253, s8, 12
	s_sub_i32 s3, s9, s8
	s_cmp_lt_i32 s3, 2
	v_writelane_b32 v253, s9, 13
	s_cbranch_scc1 .LBB0_7
	v_and_b32_e32 v1, 0x3ff, v0
	v_cmp_eq_u32_e32 vcc, 0, v1
	s_and_saveexec_b64 s[4:5], vcc
	s_cbranch_execz .LBB0_3
	s_mov_b64 s[6:7], src_shared_base
	v_mov_b32_e32 v2, 0
	v_mov_b32_e32 v3, s7
	v_mov_b32_e32 v4, 4
	v_mov_b32_e32 v5, s7
	flat_store_dword v[2:3], v2 sc0 sc1
	s_waitcnt vmcnt(0)
	flat_store_dword v[4:5], v2 sc0 sc1
	s_waitcnt vmcnt(0)

; DI unsigned xb_ld(unsigned* p) { return __hip_atomic_load(p, __ATOMIC_RELAXED, __HIP_MEMORY_SCOPE_AGENT); }
; DI unsigned xb_xcc_id() { return (unsigned)__builtin_amdgcn_s_getreg((3 << 11) | 20) & 0xFu; }
; DI void phase_peer_v(const Params& p, char* smem) {
;   const int tid = threadIdx.x, lane = tid & 63, wave = tid >> 6;
;   const int pg = lane >> 3, cq = lane & 7;
;   const unsigned xcc = xb_xcc_id() & 7u;
;   volatile int* qslot = (volatile int*)smem;
;   unsigned* cnt = p.bar + 4096 + 16;
;   for (int pi = 0; pi < 8; pi++) {
;     const int slice = (int)((xcc + (unsigned)pi) & 7u);
;     const unsigned char* vbase = p.vb8 + (size_t)slice * 16384 * 128 + cq * 16;
;     for (;;) {
;       __syncthreads();
;       if (tid == 0) {
;         const unsigned c0 = (pi >= 1) ? xb_ld(&cnt[slice]) : 0u;
;         qslot[0] = (c0 >= 64u) ? 64 : (int)atomicAdd(&cnt[slice], 1u);
;       }
;       __syncthreads();
;       const int tile = qslot[0];
;       if (tile >= 64) break;
;       const int tb = tile * 256 + wave * 64;
;       int e0a = p.experts[(size_t)tb * 128 + lane], e0b = p.experts[(size_t)tb * 128 + 64 + lane];
;       float a0a = peer_act(p, (size_t)tb * 128 + lane), a0b = peer_act(p, (size_t)tb * 128 + 64 + lane);
;       int e1a = p.experts[(size_t)(tb + 1) * 128 + lane], e1b = p.experts[(size_t)(tb + 1) * 128 + 64 + lane];
;       float pa[8], pb[8], gpa, gpb, spa, spb;
; #pragma unroll
;       for (int k = 0; k < 8; k++) { pa[k] = p.part[(size_t)k * T_TOK * 128 + (size_t)(tb + 1) * 128 + lane]; pb[k] = p.part[(size_t)k * T_TOK * 128 + (size_t)(tb + 1) * 128 + 64 + lane]; }
;       gpa = p.gates[(size_t)(tb + 1) * 128 + lane]; gpb = p.gates[(size_t)(tb + 1) * 128 + 64 + lane];
;       spa = p.usc[(size_t)(tb + 1) * 128 + lane]; spb = p.usc[(size_t)(tb + 1) * 128 + 64 + lane];
.LBB0_1395:
	s_cmp_gt_i32 s48, 10
	s_cselect_b64 s[0:1], -1, 0
	s_cmp_lt_i32 s49, 11
	s_cselect_b64 s[2:3], -1, 0
	s_or_b64 s[0:1], s[0:1], s[2:3]
	s_and_b64 vcc, exec, s[0:1]
	s_cbranch_vccnz .LBB0_1474
	v_and_b32_e32 v1, 0x3ff, v0
	v_and_b32_e32 v2, 63, v1
	v_lshlrev_b32_e32 v3, 4, v2
	v_and_b32_e32 v3, 0x70, v3
	v_lshrrev_b32_e32 v4, 3, v2
	v_lshrrev_b32_e32 v5, 6, v1
	v_readlane_b32 s2, v253, 10
	v_readlane_b32 s3, v253, 11
	v_readlane_b32 s33, v253, 8
	s_sub_u32 s2, s2, 0x1c8
	s_subb_u32 s3, s3, 0
	s_load_dwordx2 s[4:5], s[2:3], 0x88
	s_load_dwordx2 s[6:7], s[2:3], 0x190
	s_load_dwordx2 s[8:9], s[2:3], 0x1b0
	s_load_dwordx2 s[10:11], s[2:3], 0x1a8
	s_load_dwordx2 s[12:13], s[2:3], 0x150
	s_load_dwordx2 s[14:15], s[2:3], 0x1b8
	s_getreg_b32 s16, hwreg(HW_REG_XCC_ID, 0, 4)
	s_and_b32 s16, s16, 7
	v_lshlrev_b32_e32 v228, 13, v5
	v_add_u32_e32 v228, 0x400, v228
	v_and_b32_e32 v6, 7, v2
	v_lshlrev_b32_e32 v6, 4, v6
	v_add_u32_e32 v6, v6, v4
	v_lshl_add_u32 v229, v6, 2, v228
	v_lshl_add_u32 v228, v4, 6, v228
	v_xor_b32_e32 v230, 16, v2
	v_lshlrev_b32_e32 v230, 2, v230
	v_lshrrev_b32_e32 v6, 2, v2
	v_and_b32_e32 v6, 14, v6
	v_add_u32_e32 v6, v6, v3
	v_lshlrev_b32_e32 v231, 2, v6
	v_lshlrev_b32_e32 v237, 2, v2
	v_and_b32_e32 v6, 16, v2
	v_cmp_eq_u32_e64 s[52:53], 0, v6
	v_and_b32_e32 v6, 8, v2
	v_cmp_eq_u32_e64 s[54:55], 0, v6
	v_readfirstlane_b32 s34, v5
	s_lshl_b32 s34, s34, 3
	s_mov_b32 s18, s100
	s_waitcnt lgkmcnt(0)
.Lp10_group:
	s_lshl_b32 s19, s18, 5
	s_add_u32 s19, s19, s34
	s_add_u32 s35, s19, 0
	s_lshl_b32 s35, s35, 9
	s_add_u32 s36, s8, s35
	s_addc_u32 s37, s9, 0
	global_load_dword v140, v237, s[36:37]
	global_load_dword v141, v237, s[36:37] offset:256
	s_add_u32 s36, s36, 0x800000
	s_addc_u32 s37, s37, 0
	global_load_dword v142, v237, s[36:37]
	global_load_dword v143, v237, s[36:37] offset:256
	s_add_u32 s36, s36, 0x800000
	s_addc_u32 s37, s37, 0
	global_load_dword v144, v237, s[36:37]
	global_load_dword v145, v237, s[36:37] offset:256
	s_add_u32 s36, s36, 0x800000
	s_addc_u32 s37, s37, 0
	global_load_dword v146, v237, s[36:37]
	global_load_dword v147, v237, s[36:37] offset:256
	s_add_u32 s36, s36, 0x800000
	s_addc_u32 s37, s37, 0
	global_load_dword v148, v237, s[36:37]
	global_load_dword v149, v237, s[36:37] offset:256
	s_add_u32 s36, s36, 0x800000
	s_addc_u32 s37, s37, 0
	global_load_dword v150, v237, s[36:37]
	global_load_dword v151, v237, s[36:37] offset:256
	s_add_u32 s36, s36, 0x800000
	s_addc_u32 s37, s37, 0
	global_load_dword v152, v237, s[36:37]
	global_load_dword v153, v237, s[36:37] offset:256
	s_add_u32 s36, s36, 0x800000
	s_addc_u32 s37, s37, 0
	global_load_dword v154, v237, s[36:37]
	global_load_dword v155, v237, s[36:37] offset:256
	s_add_u32 s36, s10, s35
	s_addc_u32 s37, s11, 0
	global_load_dword v156, v237, s[36:37]
	global_load_dword v157, v237, s[36:37] offset:256
	s_add_u32 s36, s12, s35
	s_addc_u32 s37, s13, 0
	global_load_dword v158, v237, s[36:37]
	global_load_dword v159, v237, s[36:37] offset:256
	s_add_u32 s36, s14, s35
	s_addc_u32 s37, s15, 0
	global_load_dword v160, v237, s[36:37]
	global_load_dword v161, v237, s[36:37] offset:256
	s_add_u32 s35, s19, 1
	s_lshl_b32 s35, s35, 9
	s_add_u32 s36, s8, s35
	s_addc_u32 s37, s9, 0
	global_load_dword v162, v237, s[36:37]
	global_load_dword v163, v237, s[36:37] offset:256
	s_add_u32 s36, s36, 0x800000
	s_addc_u32 s37, s37, 0
	global_load_dword v164, v237, s[36:37]
	global_load_dword v165, v237, s[36:37] offset:256
	s_add_u32 s36, s36, 0x800000
	s_addc_u32 s37, s37, 0
	global_load_dword v166, v237, s[36:37]
	global_load_dword v167, v237, s[36:37] offset:256
	s_add_u32 s36, s36, 0x800000
	s_addc_u32 s37, s37, 0
	global_load_dword v168, v237, s[36:37]
	global_load_dword v169, v237, s[36:37] offset:256
	s_add_u32 s36, s36, 0x800000
	s_addc_u32 s37, s37, 0
	global_load_dword v170, v237, s[36:37]
	global_load_dword v171, v237, s[36:37] offset:256
	s_add_u32 s36, s36, 0x800000
	s_addc_u32 s37, s37, 0
	global_load_dword v172, v237, s[36:37]
	global_load_dword v173, v237, s[36:37] offset:256
	s_add_u32 s36, s36, 0x800000
	s_addc_u32 s37, s37, 0
	global_load_dword v174, v237, s[36:37]
	global_load_dword v175, v237, s[36:37] offset:256
	s_add_u32 s36, s36, 0x800000
	s_addc_u32 s37, s37, 0
	global_load_dword v176, v237, s[36:37]
	global_load_dword v177, v237, s[36:37] offset:256
	s_add_u32 s36, s10, s35
	s_addc_u32 s37, s11, 0
	global_load_dword v178, v237, s[36:37]
	global_load_dword v179, v237, s[36:37] offset:256
	s_add_u32 s36, s12, s35
	s_addc_u32 s37, s13, 0
	global_load_dword v180, v237, s[36:37]
	global_load_dword v181, v237, s[36:37] offset:256
	s_add_u32 s36, s14, s35
	s_addc_u32 s37, s15, 0
	global_load_dword v182, v237, s[36:37]
	global_load_dword v183, v237, s[36:37] offset:256
	s_add_u32 s35, s19, 2
	s_lshl_b32 s35, s35, 9
	s_add_u32 s36, s8, s35
	s_addc_u32 s37, s9, 0
	global_load_dword v184, v237, s[36:37]
	global_load_dword v185, v237, s[36:37] offset:256
	s_add_u32 s36, s36, 0x800000
	s_addc_u32 s37, s37, 0
	global_load_dword v186, v237, s[36:37]
	global_load_dword v187, v237, s[36:37] offset:256
	s_add_u32 s36, s36, 0x800000
	s_addc_u32 s37, s37, 0
	global_load_dword v188, v237, s[36:37]
	global_load_dword v189, v237, s[36:37] offset:256
	s_add_u32 s36, s36, 0x800000
	s_addc_u32 s37, s37, 0
	global_load_dword v190, v237, s[36:37]
	global_load_dword v191, v237, s[36:37] offset:256
	s_add_u32 s36, s36, 0x800000
	s_addc_u32 s37, s37, 0
	global_load_dword v192, v237, s[36:37]
	global_load_dword v193, v237, s[36:37] offset:256
	s_add_u32 s36, s36, 0x800000
	s_addc_u32 s37, s37, 0
	global_load_dword v194, v237, s[36:37]
	global_load_dword v195, v237, s[36:37] offset:256
; DI float gelu_tanh(float x) {
;   const float u = 0.7978845608028654f * (x + 0.044715f * x * x * x);
;   return x / (1.f + __expf(-2.f * u));
; }
; DI float peer_act(const Params& p, size_t idx) {
;   float sacc = 0.f;
; #pragma unroll
;   for (int k = 0; k < 8; k++) sacc += p.part[(size_t)k * T_TOK * 128 + idx];
;   return gelu_tanh(sacc * p.usc[idx]) * p.gates[idx];
; }
	s_add_u32 s36, s36, 0x800000
	s_addc_u32 s37, s37, 0
	global_load_dword v196, v237, s[36:37]
	global_load_dword v197, v237, s[36:37] offset:256
	s_add_u32 s36, s36, 0x800000
	s_addc_u32 s37, s37, 0
	global_load_dword v198, v237, s[36:37]
	global_load_dword v199, v237, s[36:37] offset:256
	s_add_u32 s36, s10, s35
	s_addc_u32 s37, s11, 0
	global_load_dword v200, v237, s[36:37]
	global_load_dword v201, v237, s[36:37] offset:256
	s_add_u32 s36, s12, s35
	s_addc_u32 s37, s13, 0
	global_load_dword v202, v237, s[36:37]
	global_load_dword v203, v237, s[36:37] offset:256
	s_add_u32 s36, s14, s35
	s_addc_u32 s37, s15, 0
	global_load_dword v204, v237, s[36:37]
	global_load_dword v205, v237, s[36:37] offset:256
	s_add_u32 s35, s19, 3
	s_lshl_b32 s35, s35, 9
	s_add_u32 s36, s8, s35
	s_addc_u32 s37, s9, 0
	global_load_dword v206, v237, s[36:37]
	global_load_dword v207, v237, s[36:37] offset:256
	s_add_u32 s36, s36, 0x800000
	s_addc_u32 s37, s37, 0
	global_load_dword v208, v237, s[36:37]
	global_load_dword v209, v237, s[36:37] offset:256
	s_add_u32 s36, s36, 0x800000
	s_addc_u32 s37, s37, 0
	global_load_dword v210, v237, s[36:37]
	global_load_dword v211, v237, s[36:37] offset:256
	s_add_u32 s36, s36, 0x800000
	s_addc_u32 s37, s37, 0
	global_load_dword v212, v237, s[36:37]
	global_load_dword v213, v237, s[36:37] offset:256
	s_add_u32 s36, s36, 0x800000
	s_addc_u32 s37, s37, 0
	global_load_dword v214, v237, s[36:37]
	global_load_dword v215, v237, s[36:37] offset:256
	s_add_u32 s36, s36, 0x800000
	s_addc_u32 s37, s37, 0
	global_load_dword v216, v237, s[36:37]
	global_load_dword v217, v237, s[36:37] offset:256
	s_add_u32 s36, s36, 0x800000
	s_addc_u32 s37, s37, 0
	global_load_dword v218, v237, s[36:37]
	global_load_dword v219, v237, s[36:37] offset:256
	s_add_u32 s36, s36, 0x800000
	s_addc_u32 s37, s37, 0
	global_load_dword v220, v237, s[36:37]
	global_load_dword v221, v237, s[36:37] offset:256
	s_add_u32 s36, s10, s35
	s_addc_u32 s37, s11, 0
	global_load_dword v222, v237, s[36:37]
	global_load_dword v223, v237, s[36:37] offset:256
	s_add_u32 s36, s12, s35
	s_addc_u32 s37, s13, 0
	global_load_dword v224, v237, s[36:37]
	global_load_dword v225, v237, s[36:37] offset:256
	s_add_u32 s36, s14, s35
	s_addc_u32 s37, s15, 0
	global_load_dword v226, v237, s[36:37]
	global_load_dword v227, v237, s[36:37] offset:256
	s_waitcnt vmcnt(0)
	v_pk_add_f32 v[140:141], v[140:141], v[142:143]
	v_pk_add_f32 v[144:145], v[144:145], v[146:147]
	v_pk_add_f32 v[148:149], v[148:149], v[150:151]
	v_pk_add_f32 v[152:153], v[152:153], v[154:155]
	v_pk_add_f32 v[140:141], v[140:141], v[144:145]
	v_pk_add_f32 v[148:149], v[148:149], v[152:153]
	v_pk_add_f32 v[140:141], v[140:141], v[148:149]
	v_pk_mul_f32 v[140:141], v[156:157], v[140:141]
	v_mul_f32_e32 v142, 0x3d372713, v140
	v_mul_f32_e32 v142, v140, v142
	v_fma_f32 v142, v140, v142, v140
	v_mul_f32_e32 v142, 0x3f4c422a, v142
	v_mul_f32_e32 v142, -2.0, v142
	v_mul_f32_e32 v142, 0x3fb8aa3b, v142
	v_exp_f32_e32 v142, v142
	s_nop 0
	v_add_f32_e32 v143, 1.0, v142
	v_div_scale_f32 v144, s[56:57], v143, v143, v140
	v_rcp_f32_e32 v145, v144
	s_nop 0
	v_fma_f32 v146, -v144, v145, 1.0
	v_fmac_f32_e32 v145, v146, v145
	v_div_scale_f32 v146, vcc, v140, v143, v140
	v_mul_f32_e32 v147, v146, v145
	v_fma_f32 v148, -v144, v147, v146
	v_fmac_f32_e32 v147, v148, v145
	v_fma_f32 v144, -v144, v147, v146
	v_div_fmas_f32 v144, v144, v145, v147
	v_div_fixup_f32 v149, v144, v143, v140
	v_mul_f32_e32 v142, 0x3d372713, v141
	v_mul_f32_e32 v142, v141, v142
	v_fma_f32 v142, v141, v142, v141
	v_mul_f32_e32 v142, 0x3f4c422a, v142
	v_mul_f32_e32 v142, -2.0, v142
	v_mul_f32_e32 v142, 0x3fb8aa3b, v142
	v_exp_f32_e32 v142, v142
	s_nop 0
	v_add_f32_e32 v143, 1.0, v142
	v_div_scale_f32 v144, s[56:57], v143, v143, v141
	v_rcp_f32_e32 v145, v144
	s_nop 0
	v_fma_f32 v146, -v144, v145, 1.0
	v_fmac_f32_e32 v145, v146, v145
	v_div_scale_f32 v146, vcc, v141, v143, v141
	v_mul_f32_e32 v147, v146, v145
	v_fma_f32 v148, -v144, v147, v146
	v_fmac_f32_e32 v147, v148, v145
	v_fma_f32 v144, -v144, v147, v146
	v_div_fmas_f32 v144, v144, v145, v147
	v_div_fixup_f32 v150, v144, v143, v141
	v_mul_f32_e32 v149, v149, v158
	v_mul_f32_e32 v150, v150, v159
	v_lshlrev_b32_e32 v160, 7, v160
	v_lshlrev_b32_e32 v161, 7, v161
	ds_write_b32 v229, v149 offset:0
	ds_write_b32 v229, v150 offset:32
	ds_write_b32 v229, v160 offset:4096
	ds_write_b32 v229, v161 offset:4128
	v_pk_add_f32 v[162:163], v[162:163], v[164:165]
	v_pk_add_f32 v[166:167], v[166:167], v[168:169]
	v_pk_add_f32 v[170:171], v[170:171], v[172:173]
	v_pk_add_f32 v[174:175], v[174:175], v[176:177]
	v_pk_add_f32 v[162:163], v[162:163], v[166:167]
	v_pk_add_f32 v[170:171], v[170:171], v[174:175]
	v_pk_add_f32 v[162:163], v[162:163], v[170:171]
	v_pk_mul_f32 v[162:163], v[178:179], v[162:163]
	v_mul_f32_e32 v164, 0x3d372713, v162
	v_mul_f32_e32 v164, v162, v164
	v_fma_f32 v164, v162, v164, v162
	v_mul_f32_e32 v164, 0x3f4c422a, v164
	v_mul_f32_e32 v164, -2.0, v164
	v_mul_f32_e32 v164, 0x3fb8aa3b, v164
	v_exp_f32_e32 v164, v164
	s_nop 0
	v_add_f32_e32 v165, 1.0, v164
	v_div_scale_f32 v166, s[56:57], v165, v165, v162
	v_rcp_f32_e32 v167, v166
	s_nop 0
	v_fma_f32 v168, -v166, v167, 1.0
	v_fmac_f32_e32 v167, v168, v167
	v_div_scale_f32 v168, vcc, v162, v165, v162
	v_mul_f32_e32 v169, v168, v167
	v_fma_f32 v170, -v166, v169, v168
	v_fmac_f32_e32 v169, v170, v167
	v_fma_f32 v166, -v166, v169, v168
	v_div_fmas_f32 v166, v166, v167, v169
	v_div_fixup_f32 v171, v166, v165, v162
	v_mul_f32_e32 v164, 0x3d372713, v163
	v_mul_f32_e32 v164, v163, v164
	v_fma_f32 v164, v163, v164, v163
	v_mul_f32_e32 v164, 0x3f4c422a, v164
	v_mul_f32_e32 v164, -2.0, v164
; DI float gelu_tanh(float x) {
;   const float u = 0.7978845608028654f * (x + 0.044715f * x * x * x);
;   return x / (1.f + __expf(-2.f * u));
; }
; DI float peer_act(const Params& p, size_t idx) {
;   float sacc = 0.f;
; #pragma unroll
;   for (int k = 0; k < 8; k++) sacc += p.part[(size_t)k * T_TOK * 128 + idx];
;   return gelu_tanh(sacc * p.usc[idx]) * p.gates[idx];
; }
	v_mul_f32_e32 v164, 0x3fb8aa3b, v164
	v_exp_f32_e32 v164, v164
	s_nop 0
	v_add_f32_e32 v165, 1.0, v164
	v_div_scale_f32 v166, s[56:57], v165, v165, v163
	v_rcp_f32_e32 v167, v166
	s_nop 0
	v_fma_f32 v168, -v166, v167, 1.0
	v_fmac_f32_e32 v167, v168, v167
	v_div_scale_f32 v168, vcc, v163, v165, v163
	v_mul_f32_e32 v169, v168, v167
	v_fma_f32 v170, -v166, v169, v168
	v_fmac_f32_e32 v169, v170, v167
	v_fma_f32 v166, -v166, v169, v168
	v_div_fmas_f32 v166, v166, v167, v169
	v_div_fixup_f32 v172, v166, v165, v163
	v_mul_f32_e32 v171, v171, v180
	v_mul_f32_e32 v172, v172, v181
	v_lshlrev_b32_e32 v182, 7, v182
	v_lshlrev_b32_e32 v183, 7, v183
	ds_write_b32 v229, v171 offset:512
	ds_write_b32 v229, v172 offset:544
	ds_write_b32 v229, v182 offset:4608
	ds_write_b32 v229, v183 offset:4640
	v_pk_add_f32 v[184:185], v[184:185], v[186:187]
	v_pk_add_f32 v[188:189], v[188:189], v[190:191]
	v_pk_add_f32 v[192:193], v[192:193], v[194:195]
	v_pk_add_f32 v[196:197], v[196:197], v[198:199]
	v_pk_add_f32 v[184:185], v[184:185], v[188:189]
	v_pk_add_f32 v[192:193], v[192:193], v[196:197]
	v_pk_add_f32 v[184:185], v[184:185], v[192:193]
	v_pk_mul_f32 v[184:185], v[200:201], v[184:185]
	v_mul_f32_e32 v186, 0x3d372713, v184
	v_mul_f32_e32 v186, v184, v186
	v_fma_f32 v186, v184, v186, v184
	v_mul_f32_e32 v186, 0x3f4c422a, v186
	v_mul_f32_e32 v186, -2.0, v186
	v_mul_f32_e32 v186, 0x3fb8aa3b, v186
	v_exp_f32_e32 v186, v186
	s_nop 0
	v_add_f32_e32 v187, 1.0, v186
	v_div_scale_f32 v188, s[56:57], v187, v187, v184
	v_rcp_f32_e32 v189, v188
	s_nop 0
	v_fma_f32 v190, -v188, v189, 1.0
	v_fmac_f32_e32 v189, v190, v189
	v_div_scale_f32 v190, vcc, v184, v187, v184
	v_mul_f32_e32 v191, v190, v189
	v_fma_f32 v192, -v188, v191, v190
	v_fmac_f32_e32 v191, v192, v189
	v_fma_f32 v188, -v188, v191, v190
	v_div_fmas_f32 v188, v188, v189, v191
	v_div_fixup_f32 v193, v188, v187, v184
	v_mul_f32_e32 v186, 0x3d372713, v185
	v_mul_f32_e32 v186, v185, v186
	v_fma_f32 v186, v185, v186, v185
	v_mul_f32_e32 v186, 0x3f4c422a, v186
	v_mul_f32_e32 v186, -2.0, v186
	v_mul_f32_e32 v186, 0x3fb8aa3b, v186
	v_exp_f32_e32 v186, v186
	s_nop 0
	v_add_f32_e32 v187, 1.0, v186
	v_div_scale_f32 v188, s[56:57], v187, v187, v185
	v_rcp_f32_e32 v189, v188
	s_nop 0
	v_fma_f32 v190, -v188, v189, 1.0
	v_fmac_f32_e32 v189, v190, v189
	v_div_scale_f32 v190, vcc, v185, v187, v185
	v_mul_f32_e32 v191, v190, v189
	v_fma_f32 v192, -v188, v191, v190
	v_fmac_f32_e32 v191, v192, v189
	v_fma_f32 v188, -v188, v191, v190
	v_div_fmas_f32 v188, v188, v189, v191
	v_div_fixup_f32 v194, v188, v187, v185
	v_mul_f32_e32 v193, v193, v202
	v_mul_f32_e32 v194, v194, v203
	v_lshlrev_b32_e32 v204, 7, v204
	v_lshlrev_b32_e32 v205, 7, v205
	ds_write_b32 v229, v193 offset:1024
	ds_write_b32 v229, v194 offset:1056
	ds_write_b32 v229, v204 offset:5120
	ds_write_b32 v229, v205 offset:5152
	v_pk_add_f32 v[206:207], v[206:207], v[208:209]
	v_pk_add_f32 v[210:211], v[210:211], v[212:213]
	v_pk_add_f32 v[214:215], v[214:215], v[216:217]
	v_pk_add_f32 v[218:219], v[218:219], v[220:221]
	v_pk_add_f32 v[206:207], v[206:207], v[210:211]
	v_pk_add_f32 v[214:215], v[214:215], v[218:219]
	v_pk_add_f32 v[206:207], v[206:207], v[214:215]
	v_pk_mul_f32 v[206:207], v[222:223], v[206:207]
	v_mul_f32_e32 v208, 0x3d372713, v206
	v_mul_f32_e32 v208, v206, v208
	v_fma_f32 v208, v206, v208, v206
	v_mul_f32_e32 v208, 0x3f4c422a, v208
	v_mul_f32_e32 v208, -2.0, v208
	v_mul_f32_e32 v208, 0x3fb8aa3b, v208
	v_exp_f32_e32 v208, v208
	s_nop 0
	v_add_f32_e32 v209, 1.0, v208
	v_div_scale_f32 v210, s[56:57], v209, v209, v206
	v_rcp_f32_e32 v211, v210
	s_nop 0
	v_fma_f32 v212, -v210, v211, 1.0
	v_fmac_f32_e32 v211, v212, v211
	v_div_scale_f32 v212, vcc, v206, v209, v206
	v_mul_f32_e32 v213, v212, v211
	v_fma_f32 v214, -v210, v213, v212
	v_fmac_f32_e32 v213, v214, v211
	v_fma_f32 v210, -v210, v213, v212
	v_div_fmas_f32 v210, v210, v211, v213
	v_div_fixup_f32 v215, v210, v209, v206
	v_mul_f32_e32 v208, 0x3d372713, v207
	v_mul_f32_e32 v208, v207, v208
	v_fma_f32 v208, v207, v208, v207
	v_mul_f32_e32 v208, 0x3f4c422a, v208
	v_mul_f32_e32 v208, -2.0, v208
	v_mul_f32_e32 v208, 0x3fb8aa3b, v208
	v_exp_f32_e32 v208, v208
	s_nop 0
	v_add_f32_e32 v209, 1.0, v208
	v_div_scale_f32 v210, s[56:57], v209, v209, v207
	v_rcp_f32_e32 v211, v210
	s_nop 0
	v_fma_f32 v212, -v210, v211, 1.0
	v_fmac_f32_e32 v211, v212, v211
	v_div_scale_f32 v212, vcc, v207, v209, v207
	v_mul_f32_e32 v213, v212, v211
	v_fma_f32 v214, -v210, v213, v212
	v_fmac_f32_e32 v213, v214, v211
	v_fma_f32 v210, -v210, v213, v212
	v_div_fmas_f32 v210, v210, v211, v213
	v_div_fixup_f32 v216, v210, v209, v207
	v_mul_f32_e32 v215, v215, v224
	v_mul_f32_e32 v216, v216, v225
	v_lshlrev_b32_e32 v226, 7, v226
	v_lshlrev_b32_e32 v227, 7, v227
	ds_write_b32 v229, v215 offset:1536
	ds_write_b32 v229, v216 offset:1568
	ds_write_b32 v229, v226 offset:5632
	ds_write_b32 v229, v227 offset:5664
	s_add_u32 s35, s19, 4
	s_lshl_b32 s35, s35, 9
	s_add_u32 s36, s8, s35
	s_addc_u32 s37, s9, 0
	global_load_dword v140, v237, s[36:37]
	global_load_dword v141, v237, s[36:37] offset:256
	s_add_u32 s36, s36, 0x800000
	s_addc_u32 s37, s37, 0
	global_load_dword v142, v237, s[36:37]
	global_load_dword v143, v237, s[36:37] offset:256
	s_add_u32 s36, s36, 0x800000
	s_addc_u32 s37, s37, 0
	global_load_dword v144, v237, s[36:37]
	global_load_dword v145, v237, s[36:37] offset:256
	s_add_u32 s36, s36, 0x800000
	s_addc_u32 s37, s37, 0
	global_load_dword v146, v237, s[36:37]
	global_load_dword v147, v237, s[36:37] offset:256
	s_add_u32 s36, s36, 0x800000
	s_addc_u32 s37, s37, 0
	global_load_dword v148, v237, s[36:37]
	global_load_dword v149, v237, s[36:37] offset:256
; DI float peer_act(const Params& p, size_t idx) {
;   float sacc = 0.f;
; #pragma unroll
;   for (int k = 0; k < 8; k++) sacc += p.part[(size_t)k * T_TOK * 128 + idx];
;   return gelu_tanh(sacc * p.usc[idx]) * p.gates[idx];
; }
; DI void phase_peer_v(const Params& p, char* smem) {
;     ...
;       int e0a = p.experts[(size_t)tb * 128 + lane], e0b = p.experts[(size_t)tb * 128 + 64 + lane];
;       float a0a = peer_act(p, (size_t)tb * 128 + lane), a0b = peer_act(p, (size_t)tb * 128 + 64 + lane);
;       int e1a = p.experts[(size_t)(tb + 1) * 128 + lane], e1b = p.experts[(size_t)(tb + 1) * 128 + 64 + lane];
;       float pa[8], pb[8], gpa, gpb, spa, spb;
; #pragma unroll
;       for (int k = 0; k < 8; k++) { pa[k] = p.part[(size_t)k * T_TOK * 128 + (size_t)(tb + 1) * 128 + lane]; pb[k] = p.part[(size_t)k * T_TOK * 128 + (size_t)(tb + 1) * 128 + 64 + lane]; }
;       gpa = p.gates[(size_t)(tb + 1) * 128 + lane]; gpb = p.gates[(size_t)(tb + 1) * 128 + 64 + lane];
;       spa = p.usc[(size_t)(tb + 1) * 128 + lane]; spb = p.usc[(size_t)(tb + 1) * 128 + 64 + lane];
	s_add_u32 s36, s36, 0x800000
	s_addc_u32 s37, s37, 0
	global_load_dword v150, v237, s[36:37]
	global_load_dword v151, v237, s[36:37] offset:256
	s_add_u32 s36, s36, 0x800000
	s_addc_u32 s37, s37, 0
	global_load_dword v152, v237, s[36:37]
	global_load_dword v153, v237, s[36:37] offset:256
	s_add_u32 s36, s36, 0x800000
	s_addc_u32 s37, s37, 0
	global_load_dword v154, v237, s[36:37]
	global_load_dword v155, v237, s[36:37] offset:256
	s_add_u32 s36, s10, s35
	s_addc_u32 s37, s11, 0
	global_load_dword v156, v237, s[36:37]
	global_load_dword v157, v237, s[36:37] offset:256
	s_add_u32 s36, s12, s35
	s_addc_u32 s37, s13, 0
	global_load_dword v158, v237, s[36:37]
	global_load_dword v159, v237, s[36:37] offset:256
	s_add_u32 s36, s14, s35
	s_addc_u32 s37, s15, 0
	global_load_dword v160, v237, s[36:37]
	global_load_dword v161, v237, s[36:37] offset:256
	s_add_u32 s35, s19, 5
	s_lshl_b32 s35, s35, 9
	s_add_u32 s36, s8, s35
	s_addc_u32 s37, s9, 0
	global_load_dword v162, v237, s[36:37]
	global_load_dword v163, v237, s[36:37] offset:256
	s_add_u32 s36, s36, 0x800000
	s_addc_u32 s37, s37, 0
	global_load_dword v164, v237, s[36:37]
	global_load_dword v165, v237, s[36:37] offset:256
	s_add_u32 s36, s36, 0x800000
	s_addc_u32 s37, s37, 0
	global_load_dword v166, v237, s[36:37]
	global_load_dword v167, v237, s[36:37] offset:256
	s_add_u32 s36, s36, 0x800000
	s_addc_u32 s37, s37, 0
	global_load_dword v168, v237, s[36:37]
	global_load_dword v169, v237, s[36:37] offset:256
	s_add_u32 s36, s36, 0x800000
	s_addc_u32 s37, s37, 0
	global_load_dword v170, v237, s[36:37]
	global_load_dword v171, v237, s[36:37] offset:256
	s_add_u32 s36, s36, 0x800000
	s_addc_u32 s37, s37, 0
	global_load_dword v172, v237, s[36:37]
	global_load_dword v173, v237, s[36:37] offset:256
	s_add_u32 s36, s36, 0x800000
	s_addc_u32 s37, s37, 0
	global_load_dword v174, v237, s[36:37]
	global_load_dword v175, v237, s[36:37] offset:256
	s_add_u32 s36, s36, 0x800000
	s_addc_u32 s37, s37, 0
	global_load_dword v176, v237, s[36:37]
	global_load_dword v177, v237, s[36:37] offset:256
	s_add_u32 s36, s10, s35
	s_addc_u32 s37, s11, 0
	global_load_dword v178, v237, s[36:37]
	global_load_dword v179, v237, s[36:37] offset:256
	s_add_u32 s36, s12, s35
	s_addc_u32 s37, s13, 0
	global_load_dword v180, v237, s[36:37]
	global_load_dword v181, v237, s[36:37] offset:256
	s_add_u32 s36, s14, s35
	s_addc_u32 s37, s15, 0
	global_load_dword v182, v237, s[36:37]
	global_load_dword v183, v237, s[36:37] offset:256
	s_add_u32 s35, s19, 6
	s_lshl_b32 s35, s35, 9
	s_add_u32 s36, s8, s35
	s_addc_u32 s37, s9, 0
	global_load_dword v184, v237, s[36:37]
	global_load_dword v185, v237, s[36:37] offset:256
	s_add_u32 s36, s36, 0x800000
	s_addc_u32 s37, s37, 0
	global_load_dword v186, v237, s[36:37]
	global_load_dword v187, v237, s[36:37] offset:256
	s_add_u32 s36, s36, 0x800000
	s_addc_u32 s37, s37, 0
	global_load_dword v188, v237, s[36:37]
	global_load_dword v189, v237, s[36:37] offset:256
	s_add_u32 s36, s36, 0x800000
	s_addc_u32 s37, s37, 0
	global_load_dword v190, v237, s[36:37]
	global_load_dword v191, v237, s[36:37] offset:256
	s_add_u32 s36, s36, 0x800000
	s_addc_u32 s37, s37, 0
	global_load_dword v192, v237, s[36:37]
	global_load_dword v193, v237, s[36:37] offset:256
	s_add_u32 s36, s36, 0x800000
	s_addc_u32 s37, s37, 0
	global_load_dword v194, v237, s[36:37]
	global_load_dword v195, v237, s[36:37] offset:256
	s_add_u32 s36, s36, 0x800000
	s_addc_u32 s37, s37, 0
	global_load_dword v196, v237, s[36:37]
	global_load_dword v197, v237, s[36:37] offset:256
	s_add_u32 s36, s36, 0x800000
	s_addc_u32 s37, s37, 0
	global_load_dword v198, v237, s[36:37]
	global_load_dword v199, v237, s[36:37] offset:256
	s_add_u32 s36, s10, s35
	s_addc_u32 s37, s11, 0
	global_load_dword v200, v237, s[36:37]
	global_load_dword v201, v237, s[36:37] offset:256
	s_add_u32 s36, s12, s35
	s_addc_u32 s37, s13, 0
	global_load_dword v202, v237, s[36:37]
	global_load_dword v203, v237, s[36:37] offset:256
	s_add_u32 s36, s14, s35
	s_addc_u32 s37, s15, 0
	global_load_dword v204, v237, s[36:37]
	global_load_dword v205, v237, s[36:37] offset:256
	s_add_u32 s35, s19, 7
	s_lshl_b32 s35, s35, 9
	s_add_u32 s36, s8, s35
	s_addc_u32 s37, s9, 0
	global_load_dword v206, v237, s[36:37]
	global_load_dword v207, v237, s[36:37] offset:256
	s_add_u32 s36, s36, 0x800000
	s_addc_u32 s37, s37, 0
	global_load_dword v208, v237, s[36:37]
	global_load_dword v209, v237, s[36:37] offset:256
	s_add_u32 s36, s36, 0x800000
	s_addc_u32 s37, s37, 0
	global_load_dword v210, v237, s[36:37]
	global_load_dword v211, v237, s[36:37] offset:256
	s_add_u32 s36, s36, 0x800000
	s_addc_u32 s37, s37, 0
	global_load_dword v212, v237, s[36:37]
	global_load_dword v213, v237, s[36:37] offset:256
	s_add_u32 s36, s36, 0x800000
	s_addc_u32 s37, s37, 0
	global_load_dword v214, v237, s[36:37]
	global_load_dword v215, v237, s[36:37] offset:256
	s_add_u32 s36, s36, 0x800000
	s_addc_u32 s37, s37, 0
	global_load_dword v216, v237, s[36:37]
	global_load_dword v217, v237, s[36:37] offset:256
	s_add_u32 s36, s36, 0x800000
	s_addc_u32 s37, s37, 0
	global_load_dword v218, v237, s[36:37]
	global_load_dword v219, v237, s[36:37] offset:256
	s_add_u32 s36, s36, 0x800000
	s_addc_u32 s37, s37, 0
	global_load_dword v220, v237, s[36:37]
	global_load_dword v221, v237, s[36:37] offset:256
	s_add_u32 s36, s10, s35
	s_addc_u32 s37, s11, 0
	global_load_dword v222, v237, s[36:37]
	global_load_dword v223, v237, s[36:37] offset:256
	s_add_u32 s36, s12, s35
	s_addc_u32 s37, s13, 0
	global_load_dword v224, v237, s[36:37]
	global_load_dword v225, v237, s[36:37] offset:256
	s_add_u32 s36, s14, s35
	s_addc_u32 s37, s15, 0
	global_load_dword v226, v237, s[36:37]
	global_load_dword v227, v237, s[36:37] offset:256
	s_waitcnt vmcnt(0)
; DI float gelu_tanh(float x) {
;   const float u = 0.7978845608028654f * (x + 0.044715f * x * x * x);
;   return x / (1.f + __expf(-2.f * u));
; }
; DI float peer_act(const Params& p, size_t idx) {
;   float sacc = 0.f;
; #pragma unroll
;   for (int k = 0; k < 8; k++) sacc += p.part[(size_t)k * T_TOK * 128 + idx];
;   return gelu_tanh(sacc * p.usc[idx]) * p.gates[idx];
; }
	v_pk_add_f32 v[140:141], v[140:141], v[142:143]
	v_pk_add_f32 v[144:145], v[144:145], v[146:147]
	v_pk_add_f32 v[148:149], v[148:149], v[150:151]
	v_pk_add_f32 v[152:153], v[152:153], v[154:155]
	v_pk_add_f32 v[140:141], v[140:141], v[144:145]
	v_pk_add_f32 v[148:149], v[148:149], v[152:153]
	v_pk_add_f32 v[140:141], v[140:141], v[148:149]
	v_pk_mul_f32 v[140:141], v[156:157], v[140:141]
	v_mul_f32_e32 v142, 0x3d372713, v140
	v_mul_f32_e32 v142, v140, v142
	v_fma_f32 v142, v140, v142, v140
	v_mul_f32_e32 v142, 0x3f4c422a, v142
	v_mul_f32_e32 v142, -2.0, v142
	v_mul_f32_e32 v142, 0x3fb8aa3b, v142
	v_exp_f32_e32 v142, v142
	s_nop 0
	v_add_f32_e32 v143, 1.0, v142
	v_div_scale_f32 v144, s[56:57], v143, v143, v140
	v_rcp_f32_e32 v145, v144
	s_nop 0
	v_fma_f32 v146, -v144, v145, 1.0
	v_fmac_f32_e32 v145, v146, v145
	v_div_scale_f32 v146, vcc, v140, v143, v140
	v_mul_f32_e32 v147, v146, v145
	v_fma_f32 v148, -v144, v147, v146
	v_fmac_f32_e32 v147, v148, v145
	v_fma_f32 v144, -v144, v147, v146
	v_div_fmas_f32 v144, v144, v145, v147
	v_div_fixup_f32 v149, v144, v143, v140
	v_mul_f32_e32 v142, 0x3d372713, v141
	v_mul_f32_e32 v142, v141, v142
	v_fma_f32 v142, v141, v142, v141
	v_mul_f32_e32 v142, 0x3f4c422a, v142
	v_mul_f32_e32 v142, -2.0, v142
	v_mul_f32_e32 v142, 0x3fb8aa3b, v142
	v_exp_f32_e32 v142, v142
	s_nop 0
	v_add_f32_e32 v143, 1.0, v142
	v_div_scale_f32 v144, s[56:57], v143, v143, v141
	v_rcp_f32_e32 v145, v144
	s_nop 0
	v_fma_f32 v146, -v144, v145, 1.0
	v_fmac_f32_e32 v145, v146, v145
	v_div_scale_f32 v146, vcc, v141, v143, v141
	v_mul_f32_e32 v147, v146, v145
	v_fma_f32 v148, -v144, v147, v146
	v_fmac_f32_e32 v147, v148, v145
	v_fma_f32 v144, -v144, v147, v146
	v_div_fmas_f32 v144, v144, v145, v147
	v_div_fixup_f32 v150, v144, v143, v141
	v_mul_f32_e32 v149, v149, v158
	v_mul_f32_e32 v150, v150, v159
	v_lshlrev_b32_e32 v160, 7, v160
	v_lshlrev_b32_e32 v161, 7, v161
	ds_write_b32 v229, v149 offset:2048
	ds_write_b32 v229, v150 offset:2080
	ds_write_b32 v229, v160 offset:6144
	ds_write_b32 v229, v161 offset:6176
	v_pk_add_f32 v[162:163], v[162:163], v[164:165]
	v_pk_add_f32 v[166:167], v[166:167], v[168:169]
	v_pk_add_f32 v[170:171], v[170:171], v[172:173]
	v_pk_add_f32 v[174:175], v[174:175], v[176:177]
	v_pk_add_f32 v[162:163], v[162:163], v[166:167]
	v_pk_add_f32 v[170:171], v[170:171], v[174:175]
	v_pk_add_f32 v[162:163], v[162:163], v[170:171]
	v_pk_mul_f32 v[162:163], v[178:179], v[162:163]
	v_mul_f32_e32 v164, 0x3d372713, v162
	v_mul_f32_e32 v164, v162, v164
	v_fma_f32 v164, v162, v164, v162
	v_mul_f32_e32 v164, 0x3f4c422a, v164
	v_mul_f32_e32 v164, -2.0, v164
	v_mul_f32_e32 v164, 0x3fb8aa3b, v164
	v_exp_f32_e32 v164, v164
	s_nop 0
	v_add_f32_e32 v165, 1.0, v164
	v_div_scale_f32 v166, s[56:57], v165, v165, v162
	v_rcp_f32_e32 v167, v166
	s_nop 0
	v_fma_f32 v168, -v166, v167, 1.0
	v_fmac_f32_e32 v167, v168, v167
	v_div_scale_f32 v168, vcc, v162, v165, v162
	v_mul_f32_e32 v169, v168, v167
	v_fma_f32 v170, -v166, v169, v168
	v_fmac_f32_e32 v169, v170, v167
	v_fma_f32 v166, -v166, v169, v168
	v_div_fmas_f32 v166, v166, v167, v169
	v_div_fixup_f32 v171, v166, v165, v162
	v_mul_f32_e32 v164, 0x3d372713, v163
	v_mul_f32_e32 v164, v163, v164
	v_fma_f32 v164, v163, v164, v163
	v_mul_f32_e32 v164, 0x3f4c422a, v164
	v_mul_f32_e32 v164, -2.0, v164
	v_mul_f32_e32 v164, 0x3fb8aa3b, v164
	v_exp_f32_e32 v164, v164
	s_nop 0
	v_add_f32_e32 v165, 1.0, v164
	v_div_scale_f32 v166, s[56:57], v165, v165, v163
	v_rcp_f32_e32 v167, v166
	s_nop 0
	v_fma_f32 v168, -v166, v167, 1.0
	v_fmac_f32_e32 v167, v168, v167
	v_div_scale_f32 v168, vcc, v163, v165, v163
	v_mul_f32_e32 v169, v168, v167
	v_fma_f32 v170, -v166, v169, v168
	v_fmac_f32_e32 v169, v170, v167
	v_fma_f32 v166, -v166, v169, v168
	v_div_fmas_f32 v166, v166, v167, v169
	v_div_fixup_f32 v172, v166, v165, v163
	v_mul_f32_e32 v171, v171, v180
	v_mul_f32_e32 v172, v172, v181
	v_lshlrev_b32_e32 v182, 7, v182
	v_lshlrev_b32_e32 v183, 7, v183
	ds_write_b32 v229, v171 offset:2560
	ds_write_b32 v229, v172 offset:2592
	ds_write_b32 v229, v182 offset:6656
	ds_write_b32 v229, v183 offset:6688
	v_pk_add_f32 v[184:185], v[184:185], v[186:187]
	v_pk_add_f32 v[188:189], v[188:189], v[190:191]
	v_pk_add_f32 v[192:193], v[192:193], v[194:195]
	v_pk_add_f32 v[196:197], v[196:197], v[198:199]
	v_pk_add_f32 v[184:185], v[184:185], v[188:189]
	v_pk_add_f32 v[192:193], v[192:193], v[196:197]
	v_pk_add_f32 v[184:185], v[184:185], v[192:193]
	v_pk_mul_f32 v[184:185], v[200:201], v[184:185]
	v_mul_f32_e32 v186, 0x3d372713, v184
	v_mul_f32_e32 v186, v184, v186
	v_fma_f32 v186, v184, v186, v184
	v_mul_f32_e32 v186, 0x3f4c422a, v186
	v_mul_f32_e32 v186, -2.0, v186
	v_mul_f32_e32 v186, 0x3fb8aa3b, v186
	v_exp_f32_e32 v186, v186
	s_nop 0
	v_add_f32_e32 v187, 1.0, v186
	v_div_scale_f32 v188, s[56:57], v187, v187, v184
	v_rcp_f32_e32 v189, v188
	s_nop 0
	v_fma_f32 v190, -v188, v189, 1.0
	v_fmac_f32_e32 v189, v190, v189
	v_div_scale_f32 v190, vcc, v184, v187, v184
	v_mul_f32_e32 v191, v190, v189
	v_fma_f32 v192, -v188, v191, v190
	v_fmac_f32_e32 v191, v192, v189
	v_fma_f32 v188, -v188, v191, v190
	v_div_fmas_f32 v188, v188, v189, v191
	v_div_fixup_f32 v193, v188, v187, v184
	v_mul_f32_e32 v186, 0x3d372713, v185
	v_mul_f32_e32 v186, v185, v186
	v_fma_f32 v186, v185, v186, v185
	v_mul_f32_e32 v186, 0x3f4c422a, v186
	v_mul_f32_e32 v186, -2.0, v186
	v_mul_f32_e32 v186, 0x3fb8aa3b, v186
	v_exp_f32_e32 v186, v186
	s_nop 0
	v_add_f32_e32 v187, 1.0, v186
	v_div_scale_f32 v188, s[56:57], v187, v187, v185
	v_rcp_f32_e32 v189, v188
	s_nop 0
	v_fma_f32 v190, -v188, v189, 1.0
	v_fmac_f32_e32 v189, v190, v189
	v_div_scale_f32 v190, vcc, v185, v187, v185
; DI float peer_act(const Params& p, size_t idx) {
;   float sacc = 0.f;
; #pragma unroll
;   for (int k = 0; k < 8; k++) sacc += p.part[(size_t)k * T_TOK * 128 + idx];
;   return gelu_tanh(sacc * p.usc[idx]) * p.gates[idx];
; }
; DI void phase_peer_v(const Params& p, char* smem) {
;     ...
;       u32x4 R0[16], R1[16];
; #pragma unroll
;       for (int i = 0; i < 16; i++) {
;         const int e = __shfl(i < 8 ? e0a : e0b, 8 * (i & 7) + pg);
;         R0[i] = *(const u32x4*)(vbase + (size_t)e * 128);
;       }
	v_mul_f32_e32 v191, v190, v189
	v_fma_f32 v192, -v188, v191, v190
	v_fmac_f32_e32 v191, v192, v189
	v_fma_f32 v188, -v188, v191, v190
	v_div_fmas_f32 v188, v188, v189, v191
	v_div_fixup_f32 v194, v188, v187, v185
	v_mul_f32_e32 v193, v193, v202
	v_mul_f32_e32 v194, v194, v203
	v_lshlrev_b32_e32 v204, 7, v204
	v_lshlrev_b32_e32 v205, 7, v205
	ds_write_b32 v229, v193 offset:3072
	ds_write_b32 v229, v194 offset:3104
	ds_write_b32 v229, v204 offset:7168
	ds_write_b32 v229, v205 offset:7200
	v_pk_add_f32 v[206:207], v[206:207], v[208:209]
	v_pk_add_f32 v[210:211], v[210:211], v[212:213]
	v_pk_add_f32 v[214:215], v[214:215], v[216:217]
	v_pk_add_f32 v[218:219], v[218:219], v[220:221]
	v_pk_add_f32 v[206:207], v[206:207], v[210:211]
	v_pk_add_f32 v[214:215], v[214:215], v[218:219]
	v_pk_add_f32 v[206:207], v[206:207], v[214:215]
	v_pk_mul_f32 v[206:207], v[222:223], v[206:207]
	v_mul_f32_e32 v208, 0x3d372713, v206
	v_mul_f32_e32 v208, v206, v208
	v_fma_f32 v208, v206, v208, v206
	v_mul_f32_e32 v208, 0x3f4c422a, v208
	v_mul_f32_e32 v208, -2.0, v208
	v_mul_f32_e32 v208, 0x3fb8aa3b, v208
	v_exp_f32_e32 v208, v208
	s_nop 0
	v_add_f32_e32 v209, 1.0, v208
	v_div_scale_f32 v210, s[56:57], v209, v209, v206
	v_rcp_f32_e32 v211, v210
	s_nop 0
	v_fma_f32 v212, -v210, v211, 1.0
	v_fmac_f32_e32 v211, v212, v211
	v_div_scale_f32 v212, vcc, v206, v209, v206
	v_mul_f32_e32 v213, v212, v211
	v_fma_f32 v214, -v210, v213, v212
	v_fmac_f32_e32 v213, v214, v211
	v_fma_f32 v210, -v210, v213, v212
	v_div_fmas_f32 v210, v210, v211, v213
	v_div_fixup_f32 v215, v210, v209, v206
	v_mul_f32_e32 v208, 0x3d372713, v207
	v_mul_f32_e32 v208, v207, v208
	v_fma_f32 v208, v207, v208, v207
	v_mul_f32_e32 v208, 0x3f4c422a, v208
	v_mul_f32_e32 v208, -2.0, v208
	v_mul_f32_e32 v208, 0x3fb8aa3b, v208
	v_exp_f32_e32 v208, v208
	s_nop 0
	v_add_f32_e32 v209, 1.0, v208
	v_div_scale_f32 v210, s[56:57], v209, v209, v207
	v_rcp_f32_e32 v211, v210
	s_nop 0
	v_fma_f32 v212, -v210, v211, 1.0
	v_fmac_f32_e32 v211, v212, v211
	v_div_scale_f32 v212, vcc, v207, v209, v207
	v_mul_f32_e32 v213, v212, v211
	v_fma_f32 v214, -v210, v213, v212
	v_fmac_f32_e32 v213, v214, v211
	v_fma_f32 v210, -v210, v213, v212
	v_div_fmas_f32 v210, v210, v211, v213
	v_div_fixup_f32 v216, v210, v209, v207
	v_mul_f32_e32 v215, v215, v224
	v_mul_f32_e32 v216, v216, v225
	v_lshlrev_b32_e32 v226, 7, v226
	v_lshlrev_b32_e32 v227, 7, v227
	ds_write_b32 v229, v215 offset:3584
	ds_write_b32 v229, v216 offset:3616
	ds_write_b32 v229, v226 offset:7680
	ds_write_b32 v229, v227 offset:7712
	s_waitcnt lgkmcnt(0)
	ds_read_b128 v[120:123], v228 offset:4096
	ds_read_b128 v[124:127], v228 offset:4112
	ds_read_b128 v[128:131], v228 offset:4128
	ds_read_b128 v[132:135], v228 offset:4144
	s_lshl_b32 s24, s16, 21
	s_add_u32 s20, s6, s24
	s_addc_u32 s21, s7, 0
	s_waitcnt lgkmcnt(0)
	v_or_b32_e32 v136, v120, v3
	global_load_dwordx4 v[8:11], v136, s[20:21]
	v_or_b32_e32 v137, v121, v3
	global_load_dwordx4 v[12:15], v137, s[20:21]
	v_or_b32_e32 v235, v122, v3
	global_load_dwordx4 v[16:19], v235, s[20:21]
	v_or_b32_e32 v236, v123, v3
	global_load_dwordx4 v[20:23], v236, s[20:21]
	v_or_b32_e32 v136, v124, v3
	global_load_dwordx4 v[24:27], v136, s[20:21]
	v_or_b32_e32 v137, v125, v3
	global_load_dwordx4 v[28:31], v137, s[20:21]
	v_or_b32_e32 v235, v126, v3
	global_load_dwordx4 v[32:35], v235, s[20:21]
	v_or_b32_e32 v236, v127, v3
	global_load_dwordx4 v[36:39], v236, s[20:21]
	v_or_b32_e32 v136, v128, v3
	global_load_dwordx4 v[40:43], v136, s[20:21]
	v_or_b32_e32 v137, v129, v3
	global_load_dwordx4 v[44:47], v137, s[20:21]
	v_or_b32_e32 v235, v130, v3
	global_load_dwordx4 v[48:51], v235, s[20:21]
	v_or_b32_e32 v236, v131, v3
	global_load_dwordx4 v[52:55], v236, s[20:21]
	v_or_b32_e32 v136, v132, v3
	global_load_dwordx4 v[56:59], v136, s[20:21]
	v_or_b32_e32 v137, v133, v3
	global_load_dwordx4 v[60:63], v137, s[20:21]
	v_or_b32_e32 v235, v134, v3
	global_load_dwordx4 v[64:67], v235, s[20:21]
	v_or_b32_e32 v236, v135, v3
	global_load_dwordx4 v[68:71], v236, s[20:21]
	global_load_dword v234, v231, s[4:5]
	ds_read_b128 v[104:107], v228
	ds_read_b128 v[108:111], v228 offset:16
	ds_read_b128 v[112:115], v228 offset:32
	ds_read_b128 v[116:119], v228 offset:48
	ds_read_b128 v[120:123], v228 offset:4608
	ds_read_b128 v[124:127], v228 offset:4624
	ds_read_b128 v[128:131], v228 offset:4640
	ds_read_b128 v[132:135], v228 offset:4656
	s_mov_b32 s17, 0
	s_waitcnt lgkmcnt(0)
; DI void phase_peer_v(const Params& p, char* smem) {
;     ...
;       for (int tl = 0; tl < 64; tl++) {
;         const int t = tb + tl;
;         const int t2 = tb + min(tl + 2, 63);
;         const int e2a = p.experts[(size_t)t2 * 128 + lane], e2b = p.experts[(size_t)t2 * 128 + 64 + lane];
;         const float a1a = gelu_tanh((((pa[0] + pa[1]) + (pa[2] + pa[3])) + ((pa[4] + pa[5]) + (pa[6] + pa[7]))) * spa) * gpa;
;         const float a1b = gelu_tanh((((pb[0] + pb[1]) + (pb[2] + pb[3])) + ((pb[4] + pb[5]) + (pb[6] + pb[7]))) * spb) * gpb;
; #pragma unroll
;         for (int k = 0; k < 8; k++) { pa[k] = p.part[(size_t)k * T_TOK * 128 + (size_t)t2 * 128 + lane]; pb[k] = p.part[(size_t)k * T_TOK * 128 + (size_t)t2 * 128 + 64 + lane]; }
;         gpa = p.gates[(size_t)t2 * 128 + lane]; gpb = p.gates[(size_t)t2 * 128 + 64 + lane];
;         spa = p.usc[(size_t)t2 * 128 + lane]; spb = p.usc[(size_t)t2 * 128 + 64 + lane];
;         const bool b5 = (lane & 32) != 0, b4 = (lane & 16) != 0, b3 = (lane & 8) != 0;
;         const int col = cq * 16 + (b5 ? 8 : 0) + (b4 ? 4 : 0) + (b3 ? 2 : 0);
;         float2* op = (float2*)(p.out + (size_t)t * 1024 + slice * 128 + col);
;         float2 ov = *op;
; #pragma unroll
;         for (int i = 0; i < 16; i++) {
;           const int e = __shfl(i < 8 ? e1a : e1b, 8 * (i & 7) + pg);
;           R1[i] = *(const u32x4*)(vbase + (size_t)e * 128);
;         }
;         __builtin_amdgcn_sched_barrier(0);
;         f32x2 acc[8];
; #pragma unroll
;         for (int j = 0; j < 8; j++) acc[j] = (f32x2){0.f, 0.f};
; #pragma unroll
;         for (int i = 0; i < 16; i++) {
;           const float a = __shfl(i < 8 ? a0a : a0b, 8 * (i & 7) + pg);
;           f32x2 f[8];
;           unpack_fp8x16(R0[i], f);
;           const f32x2 a2 = {a, a};
; #pragma unroll
;           for (int j = 0; j < 8; j++) acc[j] += a2 * f[j];
;         }
.Lp10_step:
	s_and_b32 s24, s17, 7
	s_lshr_b32 s25, s17, 3
	s_add_u32 s25, s25, s16
	s_and_b32 s25, s25, 7
	s_add_u32 s30, s19, s24
	s_lshl_b32 s31, s30, 12
	s_lshl_b32 s32, s25, 9
	s_add_u32 s31, s31, s32
	s_add_u32 s22, s4, s31
	s_addc_u32 s23, s5, 0
	global_load_dwordx2 v[138:139], v231, s[22:23]
	s_add_u32 s38, s17, 1
	s_and_b32 s38, s38, 63
	s_lshr_b32 s24, s38, 3
	s_add_u32 s24, s24, s16
	s_and_b32 s24, s24, 7
	s_lshl_b32 s24, s24, 21
	s_add_u32 s20, s6, s24
	s_addc_u32 s21, s7, 0
	s_waitcnt vmcnt(17)
	v_cvt_pk_f32_fp8_e32 v[72:73], v8
	v_cvt_pk_f32_fp8_sdwa v[74:75], v8 src0_sel:WORD_1
	v_cvt_pk_f32_fp8_e32 v[76:77], v9
	v_cvt_pk_f32_fp8_sdwa v[78:79], v9 src0_sel:WORD_1
	v_cvt_pk_f32_fp8_e32 v[80:81], v10
	v_cvt_pk_f32_fp8_sdwa v[82:83], v10 src0_sel:WORD_1
	v_cvt_pk_f32_fp8_e32 v[84:85], v11
	v_cvt_pk_f32_fp8_sdwa v[86:87], v11 src0_sel:WORD_1
	v_pk_mul_f32 v[88:89], v[104:105], v[72:73] op_sel_hi:[0,1]
	v_pk_mul_f32 v[90:91], v[104:105], v[74:75] op_sel_hi:[0,1]
	v_pk_mul_f32 v[92:93], v[104:105], v[76:77] op_sel_hi:[0,1]
	v_pk_mul_f32 v[94:95], v[104:105], v[78:79] op_sel_hi:[0,1]
	v_pk_mul_f32 v[96:97], v[104:105], v[80:81] op_sel_hi:[0,1]
	v_pk_mul_f32 v[98:99], v[104:105], v[82:83] op_sel_hi:[0,1]
	v_pk_mul_f32 v[100:101], v[104:105], v[84:85] op_sel_hi:[0,1]
	v_pk_mul_f32 v[102:103], v[104:105], v[86:87] op_sel_hi:[0,1]
	v_or_b32_e32 v136, v120, v3
	global_load_dwordx4 v[8:11], v136, s[20:21]
	s_waitcnt vmcnt(17)
	v_cvt_pk_f32_fp8_e32 v[72:73], v12
	v_cvt_pk_f32_fp8_sdwa v[74:75], v12 src0_sel:WORD_1
	v_cvt_pk_f32_fp8_e32 v[76:77], v13
	v_cvt_pk_f32_fp8_sdwa v[78:79], v13 src0_sel:WORD_1
	v_cvt_pk_f32_fp8_e32 v[80:81], v14
	v_cvt_pk_f32_fp8_sdwa v[82:83], v14 src0_sel:WORD_1
	v_cvt_pk_f32_fp8_e32 v[84:85], v15
	v_cvt_pk_f32_fp8_sdwa v[86:87], v15 src0_sel:WORD_1
	v_pk_fma_f32 v[88:89], v[104:105], v[72:73], v[88:89] op_sel:[1,0,0] op_sel_hi:[1,1,1]
	v_pk_fma_f32 v[90:91], v[104:105], v[74:75], v[90:91] op_sel:[1,0,0] op_sel_hi:[1,1,1]
	v_pk_fma_f32 v[92:93], v[104:105], v[76:77], v[92:93] op_sel:[1,0,0] op_sel_hi:[1,1,1]
	v_pk_fma_f32 v[94:95], v[104:105], v[78:79], v[94:95] op_sel:[1,0,0] op_sel_hi:[1,1,1]
	v_pk_fma_f32 v[96:97], v[104:105], v[80:81], v[96:97] op_sel:[1,0,0] op_sel_hi:[1,1,1]
	v_pk_fma_f32 v[98:99], v[104:105], v[82:83], v[98:99] op_sel:[1,0,0] op_sel_hi:[1,1,1]
	v_pk_fma_f32 v[100:101], v[104:105], v[84:85], v[100:101] op_sel:[1,0,0] op_sel_hi:[1,1,1]
	v_pk_fma_f32 v[102:103], v[104:105], v[86:87], v[102:103] op_sel:[1,0,0] op_sel_hi:[1,1,1]
	v_or_b32_e32 v137, v121, v3
	global_load_dwordx4 v[12:15], v137, s[20:21]
	s_waitcnt vmcnt(17)
	v_cvt_pk_f32_fp8_e32 v[72:73], v16
	v_cvt_pk_f32_fp8_sdwa v[74:75], v16 src0_sel:WORD_1
	v_cvt_pk_f32_fp8_e32 v[76:77], v17
	v_cvt_pk_f32_fp8_sdwa v[78:79], v17 src0_sel:WORD_1
	v_cvt_pk_f32_fp8_e32 v[80:81], v18
	v_cvt_pk_f32_fp8_sdwa v[82:83], v18 src0_sel:WORD_1
	v_cvt_pk_f32_fp8_e32 v[84:85], v19
	v_cvt_pk_f32_fp8_sdwa v[86:87], v19 src0_sel:WORD_1
	v_pk_fma_f32 v[88:89], v[106:107], v[72:73], v[88:89] op_sel_hi:[0,1,1]
	v_pk_fma_f32 v[90:91], v[106:107], v[74:75], v[90:91] op_sel_hi:[0,1,1]
	v_pk_fma_f32 v[92:93], v[106:107], v[76:77], v[92:93] op_sel_hi:[0,1,1]
	v_pk_fma_f32 v[94:95], v[106:107], v[78:79], v[94:95] op_sel_hi:[0,1,1]
	v_pk_fma_f32 v[96:97], v[106:107], v[80:81], v[96:97] op_sel_hi:[0,1,1]
	v_pk_fma_f32 v[98:99], v[106:107], v[82:83], v[98:99] op_sel_hi:[0,1,1]
	v_pk_fma_f32 v[100:101], v[106:107], v[84:85], v[100:101] op_sel_hi:[0,1,1]
	v_pk_fma_f32 v[102:103], v[106:107], v[86:87], v[102:103] op_sel_hi:[0,1,1]
	v_or_b32_e32 v235, v122, v3
	global_load_dwordx4 v[16:19], v235, s[20:21]
	s_waitcnt vmcnt(17)
	v_cvt_pk_f32_fp8_e32 v[72:73], v20
	v_cvt_pk_f32_fp8_sdwa v[74:75], v20 src0_sel:WORD_1
	v_cvt_pk_f32_fp8_e32 v[76:77], v21
	v_cvt_pk_f32_fp8_sdwa v[78:79], v21 src0_sel:WORD_1
	v_cvt_pk_f32_fp8_e32 v[80:81], v22
	v_cvt_pk_f32_fp8_sdwa v[82:83], v22 src0_sel:WORD_1
	v_cvt_pk_f32_fp8_e32 v[84:85], v23
	v_cvt_pk_f32_fp8_sdwa v[86:87], v23 src0_sel:WORD_1
	v_pk_fma_f32 v[88:89], v[106:107], v[72:73], v[88:89] op_sel:[1,0,0] op_sel_hi:[1,1,1]
	v_pk_fma_f32 v[90:91], v[106:107], v[74:75], v[90:91] op_sel:[1,0,0] op_sel_hi:[1,1,1]
	v_pk_fma_f32 v[92:93], v[106:107], v[76:77], v[92:93] op_sel:[1,0,0] op_sel_hi:[1,1,1]
	v_pk_fma_f32 v[94:95], v[106:107], v[78:79], v[94:95] op_sel:[1,0,0] op_sel_hi:[1,1,1]
	v_pk_fma_f32 v[96:97], v[106:107], v[80:81], v[96:97] op_sel:[1,0,0] op_sel_hi:[1,1,1]
	v_pk_fma_f32 v[98:99], v[106:107], v[82:83], v[98:99] op_sel:[1,0,0] op_sel_hi:[1,1,1]
	v_pk_fma_f32 v[100:101], v[106:107], v[84:85], v[100:101] op_sel:[1,0,0] op_sel_hi:[1,1,1]
	v_pk_fma_f32 v[102:103], v[106:107], v[86:87], v[102:103] op_sel:[1,0,0] op_sel_hi:[1,1,1]
	v_or_b32_e32 v236, v123, v3
	global_load_dwordx4 v[20:23], v236, s[20:21]
	s_waitcnt vmcnt(17)
	v_cvt_pk_f32_fp8_e32 v[72:73], v24
	v_cvt_pk_f32_fp8_sdwa v[74:75], v24 src0_sel:WORD_1
	v_cvt_pk_f32_fp8_e32 v[76:77], v25
	v_cvt_pk_f32_fp8_sdwa v[78:79], v25 src0_sel:WORD_1
	v_cvt_pk_f32_fp8_e32 v[80:81], v26
	v_cvt_pk_f32_fp8_sdwa v[82:83], v26 src0_sel:WORD_1
	v_cvt_pk_f32_fp8_e32 v[84:85], v27
	v_cvt_pk_f32_fp8_sdwa v[86:87], v27 src0_sel:WORD_1
	v_pk_fma_f32 v[88:89], v[108:109], v[72:73], v[88:89] op_sel_hi:[0,1,1]
	v_pk_fma_f32 v[90:91], v[108:109], v[74:75], v[90:91] op_sel_hi:[0,1,1]
	v_pk_fma_f32 v[92:93], v[108:109], v[76:77], v[92:93] op_sel_hi:[0,1,1]
	v_pk_fma_f32 v[94:95], v[108:109], v[78:79], v[94:95] op_sel_hi:[0,1,1]
	v_pk_fma_f32 v[96:97], v[108:109], v[80:81], v[96:97] op_sel_hi:[0,1,1]
	v_pk_fma_f32 v[98:99], v[108:109], v[82:83], v[98:99] op_sel_hi:[0,1,1]
	v_pk_fma_f32 v[100:101], v[108:109], v[84:85], v[100:101] op_sel_hi:[0,1,1]
	v_pk_fma_f32 v[102:103], v[108:109], v[86:87], v[102:103] op_sel_hi:[0,1,1]
	v_or_b32_e32 v136, v124, v3
	global_load_dwordx4 v[24:27], v136, s[20:21]
	s_waitcnt vmcnt(17)
; DI void phase_peer_v(const Params& p, char* smem) {
;     ...
; #pragma unroll
;         for (int i = 0; i < 16; i++) {
;           const float a = __shfl(i < 8 ? a0a : a0b, 8 * (i & 7) + pg);
;           f32x2 f[8];
;           unpack_fp8x16(R0[i], f);
;           const f32x2 a2 = {a, a};
; #pragma unroll
;           for (int j = 0; j < 8; j++) acc[j] += a2 * f[j];
;         }
	v_cvt_pk_f32_fp8_e32 v[72:73], v28
	v_cvt_pk_f32_fp8_sdwa v[74:75], v28 src0_sel:WORD_1
	v_cvt_pk_f32_fp8_e32 v[76:77], v29
	v_cvt_pk_f32_fp8_sdwa v[78:79], v29 src0_sel:WORD_1
	v_cvt_pk_f32_fp8_e32 v[80:81], v30
	v_cvt_pk_f32_fp8_sdwa v[82:83], v30 src0_sel:WORD_1
	v_cvt_pk_f32_fp8_e32 v[84:85], v31
	v_cvt_pk_f32_fp8_sdwa v[86:87], v31 src0_sel:WORD_1
	v_pk_fma_f32 v[88:89], v[108:109], v[72:73], v[88:89] op_sel:[1,0,0] op_sel_hi:[1,1,1]
	v_pk_fma_f32 v[90:91], v[108:109], v[74:75], v[90:91] op_sel:[1,0,0] op_sel_hi:[1,1,1]
	v_pk_fma_f32 v[92:93], v[108:109], v[76:77], v[92:93] op_sel:[1,0,0] op_sel_hi:[1,1,1]
	v_pk_fma_f32 v[94:95], v[108:109], v[78:79], v[94:95] op_sel:[1,0,0] op_sel_hi:[1,1,1]
	v_pk_fma_f32 v[96:97], v[108:109], v[80:81], v[96:97] op_sel:[1,0,0] op_sel_hi:[1,1,1]
	v_pk_fma_f32 v[98:99], v[108:109], v[82:83], v[98:99] op_sel:[1,0,0] op_sel_hi:[1,1,1]
	v_pk_fma_f32 v[100:101], v[108:109], v[84:85], v[100:101] op_sel:[1,0,0] op_sel_hi:[1,1,1]
	v_pk_fma_f32 v[102:103], v[108:109], v[86:87], v[102:103] op_sel:[1,0,0] op_sel_hi:[1,1,1]
	v_or_b32_e32 v137, v125, v3
	global_load_dwordx4 v[28:31], v137, s[20:21]
	s_waitcnt vmcnt(17)
	v_cvt_pk_f32_fp8_e32 v[72:73], v32
	v_cvt_pk_f32_fp8_sdwa v[74:75], v32 src0_sel:WORD_1
	v_cvt_pk_f32_fp8_e32 v[76:77], v33
	v_cvt_pk_f32_fp8_sdwa v[78:79], v33 src0_sel:WORD_1
	v_cvt_pk_f32_fp8_e32 v[80:81], v34
	v_cvt_pk_f32_fp8_sdwa v[82:83], v34 src0_sel:WORD_1
	v_cvt_pk_f32_fp8_e32 v[84:85], v35
	v_cvt_pk_f32_fp8_sdwa v[86:87], v35 src0_sel:WORD_1
	v_pk_fma_f32 v[88:89], v[110:111], v[72:73], v[88:89] op_sel_hi:[0,1,1]
	v_pk_fma_f32 v[90:91], v[110:111], v[74:75], v[90:91] op_sel_hi:[0,1,1]
	v_pk_fma_f32 v[92:93], v[110:111], v[76:77], v[92:93] op_sel_hi:[0,1,1]
	v_pk_fma_f32 v[94:95], v[110:111], v[78:79], v[94:95] op_sel_hi:[0,1,1]
	v_pk_fma_f32 v[96:97], v[110:111], v[80:81], v[96:97] op_sel_hi:[0,1,1]
	v_pk_fma_f32 v[98:99], v[110:111], v[82:83], v[98:99] op_sel_hi:[0,1,1]
	v_pk_fma_f32 v[100:101], v[110:111], v[84:85], v[100:101] op_sel_hi:[0,1,1]
	v_pk_fma_f32 v[102:103], v[110:111], v[86:87], v[102:103] op_sel_hi:[0,1,1]
	v_or_b32_e32 v235, v126, v3
	global_load_dwordx4 v[32:35], v235, s[20:21]
	s_waitcnt vmcnt(17)
	v_cvt_pk_f32_fp8_e32 v[72:73], v36
	v_cvt_pk_f32_fp8_sdwa v[74:75], v36 src0_sel:WORD_1
	v_cvt_pk_f32_fp8_e32 v[76:77], v37
	v_cvt_pk_f32_fp8_sdwa v[78:79], v37 src0_sel:WORD_1
	v_cvt_pk_f32_fp8_e32 v[80:81], v38
	v_cvt_pk_f32_fp8_sdwa v[82:83], v38 src0_sel:WORD_1
	v_cvt_pk_f32_fp8_e32 v[84:85], v39
	v_cvt_pk_f32_fp8_sdwa v[86:87], v39 src0_sel:WORD_1
	v_pk_fma_f32 v[88:89], v[110:111], v[72:73], v[88:89] op_sel:[1,0,0] op_sel_hi:[1,1,1]
	v_pk_fma_f32 v[90:91], v[110:111], v[74:75], v[90:91] op_sel:[1,0,0] op_sel_hi:[1,1,1]
	v_pk_fma_f32 v[92:93], v[110:111], v[76:77], v[92:93] op_sel:[1,0,0] op_sel_hi:[1,1,1]
	v_pk_fma_f32 v[94:95], v[110:111], v[78:79], v[94:95] op_sel:[1,0,0] op_sel_hi:[1,1,1]
	v_pk_fma_f32 v[96:97], v[110:111], v[80:81], v[96:97] op_sel:[1,0,0] op_sel_hi:[1,1,1]
	v_pk_fma_f32 v[98:99], v[110:111], v[82:83], v[98:99] op_sel:[1,0,0] op_sel_hi:[1,1,1]
	v_pk_fma_f32 v[100:101], v[110:111], v[84:85], v[100:101] op_sel:[1,0,0] op_sel_hi:[1,1,1]
	v_pk_fma_f32 v[102:103], v[110:111], v[86:87], v[102:103] op_sel:[1,0,0] op_sel_hi:[1,1,1]
	v_or_b32_e32 v236, v127, v3
	global_load_dwordx4 v[36:39], v236, s[20:21]
	s_waitcnt vmcnt(17)
	v_cvt_pk_f32_fp8_e32 v[72:73], v40
	v_cvt_pk_f32_fp8_sdwa v[74:75], v40 src0_sel:WORD_1
	v_cvt_pk_f32_fp8_e32 v[76:77], v41
	v_cvt_pk_f32_fp8_sdwa v[78:79], v41 src0_sel:WORD_1
	v_cvt_pk_f32_fp8_e32 v[80:81], v42
	v_cvt_pk_f32_fp8_sdwa v[82:83], v42 src0_sel:WORD_1
	v_cvt_pk_f32_fp8_e32 v[84:85], v43
	v_cvt_pk_f32_fp8_sdwa v[86:87], v43 src0_sel:WORD_1
	v_pk_fma_f32 v[88:89], v[112:113], v[72:73], v[88:89] op_sel_hi:[0,1,1]
	v_pk_fma_f32 v[90:91], v[112:113], v[74:75], v[90:91] op_sel_hi:[0,1,1]
	v_pk_fma_f32 v[92:93], v[112:113], v[76:77], v[92:93] op_sel_hi:[0,1,1]
	v_pk_fma_f32 v[94:95], v[112:113], v[78:79], v[94:95] op_sel_hi:[0,1,1]
	v_pk_fma_f32 v[96:97], v[112:113], v[80:81], v[96:97] op_sel_hi:[0,1,1]
	v_pk_fma_f32 v[98:99], v[112:113], v[82:83], v[98:99] op_sel_hi:[0,1,1]
	v_pk_fma_f32 v[100:101], v[112:113], v[84:85], v[100:101] op_sel_hi:[0,1,1]
	v_pk_fma_f32 v[102:103], v[112:113], v[86:87], v[102:103] op_sel_hi:[0,1,1]
	v_or_b32_e32 v136, v128, v3
	global_load_dwordx4 v[40:43], v136, s[20:21]
	s_waitcnt vmcnt(17)
	v_cvt_pk_f32_fp8_e32 v[72:73], v44
	v_cvt_pk_f32_fp8_sdwa v[74:75], v44 src0_sel:WORD_1
	v_cvt_pk_f32_fp8_e32 v[76:77], v45
	v_cvt_pk_f32_fp8_sdwa v[78:79], v45 src0_sel:WORD_1
	v_cvt_pk_f32_fp8_e32 v[80:81], v46
	v_cvt_pk_f32_fp8_sdwa v[82:83], v46 src0_sel:WORD_1
	v_cvt_pk_f32_fp8_e32 v[84:85], v47
	v_cvt_pk_f32_fp8_sdwa v[86:87], v47 src0_sel:WORD_1
	v_pk_fma_f32 v[88:89], v[112:113], v[72:73], v[88:89] op_sel:[1,0,0] op_sel_hi:[1,1,1]
	v_pk_fma_f32 v[90:91], v[112:113], v[74:75], v[90:91] op_sel:[1,0,0] op_sel_hi:[1,1,1]
	v_pk_fma_f32 v[92:93], v[112:113], v[76:77], v[92:93] op_sel:[1,0,0] op_sel_hi:[1,1,1]
	v_pk_fma_f32 v[94:95], v[112:113], v[78:79], v[94:95] op_sel:[1,0,0] op_sel_hi:[1,1,1]
	v_pk_fma_f32 v[96:97], v[112:113], v[80:81], v[96:97] op_sel:[1,0,0] op_sel_hi:[1,1,1]
	v_pk_fma_f32 v[98:99], v[112:113], v[82:83], v[98:99] op_sel:[1,0,0] op_sel_hi:[1,1,1]
	v_pk_fma_f32 v[100:101], v[112:113], v[84:85], v[100:101] op_sel:[1,0,0] op_sel_hi:[1,1,1]
	v_pk_fma_f32 v[102:103], v[112:113], v[86:87], v[102:103] op_sel:[1,0,0] op_sel_hi:[1,1,1]
	v_or_b32_e32 v137, v129, v3
	global_load_dwordx4 v[44:47], v137, s[20:21]
	s_waitcnt vmcnt(17)
; DI void phase_peer_v(const Params& p, char* smem) {
;     ...
; #pragma unroll
;         for (int i = 0; i < 16; i++) {
;           const float a = __shfl(i < 8 ? a0a : a0b, 8 * (i & 7) + pg);
;           f32x2 f[8];
;           unpack_fp8x16(R0[i], f);
;           const f32x2 a2 = {a, a};
; #pragma unroll
;           for (int j = 0; j < 8; j++) acc[j] += a2 * f[j];
;         }
	v_cvt_pk_f32_fp8_e32 v[72:73], v48
	v_cvt_pk_f32_fp8_sdwa v[74:75], v48 src0_sel:WORD_1
	v_cvt_pk_f32_fp8_e32 v[76:77], v49
	v_cvt_pk_f32_fp8_sdwa v[78:79], v49 src0_sel:WORD_1
	v_cvt_pk_f32_fp8_e32 v[80:81], v50
	v_cvt_pk_f32_fp8_sdwa v[82:83], v50 src0_sel:WORD_1
	v_cvt_pk_f32_fp8_e32 v[84:85], v51
	v_cvt_pk_f32_fp8_sdwa v[86:87], v51 src0_sel:WORD_1
	v_pk_fma_f32 v[88:89], v[114:115], v[72:73], v[88:89] op_sel_hi:[0,1,1]
	v_pk_fma_f32 v[90:91], v[114:115], v[74:75], v[90:91] op_sel_hi:[0,1,1]
	v_pk_fma_f32 v[92:93], v[114:115], v[76:77], v[92:93] op_sel_hi:[0,1,1]
	v_pk_fma_f32 v[94:95], v[114:115], v[78:79], v[94:95] op_sel_hi:[0,1,1]
	v_pk_fma_f32 v[96:97], v[114:115], v[80:81], v[96:97] op_sel_hi:[0,1,1]
	v_pk_fma_f32 v[98:99], v[114:115], v[82:83], v[98:99] op_sel_hi:[0,1,1]
	v_pk_fma_f32 v[100:101], v[114:115], v[84:85], v[100:101] op_sel_hi:[0,1,1]
	v_pk_fma_f32 v[102:103], v[114:115], v[86:87], v[102:103] op_sel_hi:[0,1,1]
	v_or_b32_e32 v235, v130, v3
	global_load_dwordx4 v[48:51], v235, s[20:21]
	s_waitcnt vmcnt(17)
	v_cvt_pk_f32_fp8_e32 v[72:73], v52
	v_cvt_pk_f32_fp8_sdwa v[74:75], v52 src0_sel:WORD_1
	v_cvt_pk_f32_fp8_e32 v[76:77], v53
	v_cvt_pk_f32_fp8_sdwa v[78:79], v53 src0_sel:WORD_1
	v_cvt_pk_f32_fp8_e32 v[80:81], v54
	v_cvt_pk_f32_fp8_sdwa v[82:83], v54 src0_sel:WORD_1
	v_cvt_pk_f32_fp8_e32 v[84:85], v55
	v_cvt_pk_f32_fp8_sdwa v[86:87], v55 src0_sel:WORD_1
	v_pk_fma_f32 v[88:89], v[114:115], v[72:73], v[88:89] op_sel:[1,0,0] op_sel_hi:[1,1,1]
	v_pk_fma_f32 v[90:91], v[114:115], v[74:75], v[90:91] op_sel:[1,0,0] op_sel_hi:[1,1,1]
	v_pk_fma_f32 v[92:93], v[114:115], v[76:77], v[92:93] op_sel:[1,0,0] op_sel_hi:[1,1,1]
	v_pk_fma_f32 v[94:95], v[114:115], v[78:79], v[94:95] op_sel:[1,0,0] op_sel_hi:[1,1,1]
	v_pk_fma_f32 v[96:97], v[114:115], v[80:81], v[96:97] op_sel:[1,0,0] op_sel_hi:[1,1,1]
	v_pk_fma_f32 v[98:99], v[114:115], v[82:83], v[98:99] op_sel:[1,0,0] op_sel_hi:[1,1,1]
	v_pk_fma_f32 v[100:101], v[114:115], v[84:85], v[100:101] op_sel:[1,0,0] op_sel_hi:[1,1,1]
	v_pk_fma_f32 v[102:103], v[114:115], v[86:87], v[102:103] op_sel:[1,0,0] op_sel_hi:[1,1,1]
	v_or_b32_e32 v236, v131, v3
	global_load_dwordx4 v[52:55], v236, s[20:21]
	s_waitcnt vmcnt(17)
	v_cvt_pk_f32_fp8_e32 v[72:73], v56
	v_cvt_pk_f32_fp8_sdwa v[74:75], v56 src0_sel:WORD_1
	v_cvt_pk_f32_fp8_e32 v[76:77], v57
	v_cvt_pk_f32_fp8_sdwa v[78:79], v57 src0_sel:WORD_1
	v_cvt_pk_f32_fp8_e32 v[80:81], v58
	v_cvt_pk_f32_fp8_sdwa v[82:83], v58 src0_sel:WORD_1
	v_cvt_pk_f32_fp8_e32 v[84:85], v59
	v_cvt_pk_f32_fp8_sdwa v[86:87], v59 src0_sel:WORD_1
	v_pk_fma_f32 v[88:89], v[116:117], v[72:73], v[88:89] op_sel_hi:[0,1,1]
	v_pk_fma_f32 v[90:91], v[116:117], v[74:75], v[90:91] op_sel_hi:[0,1,1]
	v_pk_fma_f32 v[92:93], v[116:117], v[76:77], v[92:93] op_sel_hi:[0,1,1]
	v_pk_fma_f32 v[94:95], v[116:117], v[78:79], v[94:95] op_sel_hi:[0,1,1]
	v_pk_fma_f32 v[96:97], v[116:117], v[80:81], v[96:97] op_sel_hi:[0,1,1]
	v_pk_fma_f32 v[98:99], v[116:117], v[82:83], v[98:99] op_sel_hi:[0,1,1]
	v_pk_fma_f32 v[100:101], v[116:117], v[84:85], v[100:101] op_sel_hi:[0,1,1]
	v_pk_fma_f32 v[102:103], v[116:117], v[86:87], v[102:103] op_sel_hi:[0,1,1]
	v_or_b32_e32 v136, v132, v3
	global_load_dwordx4 v[56:59], v136, s[20:21]
	s_waitcnt vmcnt(17)
	v_cvt_pk_f32_fp8_e32 v[72:73], v60
	v_cvt_pk_f32_fp8_sdwa v[74:75], v60 src0_sel:WORD_1
	v_cvt_pk_f32_fp8_e32 v[76:77], v61
	v_cvt_pk_f32_fp8_sdwa v[78:79], v61 src0_sel:WORD_1
	v_cvt_pk_f32_fp8_e32 v[80:81], v62
	v_cvt_pk_f32_fp8_sdwa v[82:83], v62 src0_sel:WORD_1
	v_cvt_pk_f32_fp8_e32 v[84:85], v63
	v_cvt_pk_f32_fp8_sdwa v[86:87], v63 src0_sel:WORD_1
	v_pk_fma_f32 v[88:89], v[116:117], v[72:73], v[88:89] op_sel:[1,0,0] op_sel_hi:[1,1,1]
	v_pk_fma_f32 v[90:91], v[116:117], v[74:75], v[90:91] op_sel:[1,0,0] op_sel_hi:[1,1,1]
	v_pk_fma_f32 v[92:93], v[116:117], v[76:77], v[92:93] op_sel:[1,0,0] op_sel_hi:[1,1,1]
	v_pk_fma_f32 v[94:95], v[116:117], v[78:79], v[94:95] op_sel:[1,0,0] op_sel_hi:[1,1,1]
	v_pk_fma_f32 v[96:97], v[116:117], v[80:81], v[96:97] op_sel:[1,0,0] op_sel_hi:[1,1,1]
	v_pk_fma_f32 v[98:99], v[116:117], v[82:83], v[98:99] op_sel:[1,0,0] op_sel_hi:[1,1,1]
	v_pk_fma_f32 v[100:101], v[116:117], v[84:85], v[100:101] op_sel:[1,0,0] op_sel_hi:[1,1,1]
	v_pk_fma_f32 v[102:103], v[116:117], v[86:87], v[102:103] op_sel:[1,0,0] op_sel_hi:[1,1,1]
	v_or_b32_e32 v137, v133, v3
	global_load_dwordx4 v[60:63], v137, s[20:21]
	s_waitcnt vmcnt(17)
; DI void phase_peer_v(const Params& p, char* smem) {
;     ...
;         f32x2 r4[4], r2[2], r1;
; #pragma unroll
;         for (int j = 0; j < 4; j++) {
;           const f32x2 send = b5 ? acc[j] : acc[4 + j];
;           const f32x2 keep = b5 ? acc[4 + j] : acc[j];
;           r4[j].x = keep.x + __shfl_xor(send.x, 32); r4[j].y = keep.y + __shfl_xor(send.y, 32);
;         }
; #pragma unroll
;         for (int j = 0; j < 2; j++) {
;           const f32x2 send = b4 ? r4[j] : r4[2 + j];
;           const f32x2 keep = b4 ? r4[2 + j] : r4[j];
;           r2[j].x = keep.x + __shfl_xor(send.x, 16); r2[j].y = keep.y + __shfl_xor(send.y, 16);
;         }
;         {
;           const f32x2 send = b3 ? r2[0] : r2[1];
;           const f32x2 keep = b3 ? r2[1] : r2[0];
;           r1.x = keep.x + __shfl_xor(send.x, 8); r1.y = keep.y + __shfl_xor(send.y, 8);
;         }
;         ov.x += r1.x; ov.y += r1.y; *op = ov;
; #pragma unroll
;         for (int i = 0; i < 16; i++) R0[i] = R1[i];
;         e0a = e1a; e0b = e1b; a0a = a1a; a0b = a1b;
;         e1a = e2a; e1b = e2b;
;       }
	v_cvt_pk_f32_fp8_e32 v[72:73], v64
	v_cvt_pk_f32_fp8_sdwa v[74:75], v64 src0_sel:WORD_1
	v_cvt_pk_f32_fp8_e32 v[76:77], v65
	v_cvt_pk_f32_fp8_sdwa v[78:79], v65 src0_sel:WORD_1
	v_cvt_pk_f32_fp8_e32 v[80:81], v66
	v_cvt_pk_f32_fp8_sdwa v[82:83], v66 src0_sel:WORD_1
	v_cvt_pk_f32_fp8_e32 v[84:85], v67
	v_cvt_pk_f32_fp8_sdwa v[86:87], v67 src0_sel:WORD_1
	v_pk_fma_f32 v[88:89], v[118:119], v[72:73], v[88:89] op_sel_hi:[0,1,1]
	v_pk_fma_f32 v[90:91], v[118:119], v[74:75], v[90:91] op_sel_hi:[0,1,1]
	v_pk_fma_f32 v[92:93], v[118:119], v[76:77], v[92:93] op_sel_hi:[0,1,1]
	v_pk_fma_f32 v[94:95], v[118:119], v[78:79], v[94:95] op_sel_hi:[0,1,1]
	v_pk_fma_f32 v[96:97], v[118:119], v[80:81], v[96:97] op_sel_hi:[0,1,1]
	v_pk_fma_f32 v[98:99], v[118:119], v[82:83], v[98:99] op_sel_hi:[0,1,1]
	v_pk_fma_f32 v[100:101], v[118:119], v[84:85], v[100:101] op_sel_hi:[0,1,1]
	v_pk_fma_f32 v[102:103], v[118:119], v[86:87], v[102:103] op_sel_hi:[0,1,1]
	v_or_b32_e32 v235, v134, v3
	global_load_dwordx4 v[64:67], v235, s[20:21]
	s_waitcnt vmcnt(17)
	v_cvt_pk_f32_fp8_e32 v[72:73], v68
	v_cvt_pk_f32_fp8_sdwa v[74:75], v68 src0_sel:WORD_1
	v_cvt_pk_f32_fp8_e32 v[76:77], v69
	v_cvt_pk_f32_fp8_sdwa v[78:79], v69 src0_sel:WORD_1
	v_cvt_pk_f32_fp8_e32 v[80:81], v70
	v_cvt_pk_f32_fp8_sdwa v[82:83], v70 src0_sel:WORD_1
	v_cvt_pk_f32_fp8_e32 v[84:85], v71
	v_cvt_pk_f32_fp8_sdwa v[86:87], v71 src0_sel:WORD_1
	v_pk_fma_f32 v[88:89], v[118:119], v[72:73], v[88:89] op_sel:[1,0,0] op_sel_hi:[1,1,1]
	v_pk_fma_f32 v[90:91], v[118:119], v[74:75], v[90:91] op_sel:[1,0,0] op_sel_hi:[1,1,1]
	v_pk_fma_f32 v[92:93], v[118:119], v[76:77], v[92:93] op_sel:[1,0,0] op_sel_hi:[1,1,1]
	v_pk_fma_f32 v[94:95], v[118:119], v[78:79], v[94:95] op_sel:[1,0,0] op_sel_hi:[1,1,1]
	v_pk_fma_f32 v[96:97], v[118:119], v[80:81], v[96:97] op_sel:[1,0,0] op_sel_hi:[1,1,1]
	v_pk_fma_f32 v[98:99], v[118:119], v[82:83], v[98:99] op_sel:[1,0,0] op_sel_hi:[1,1,1]
	v_pk_fma_f32 v[100:101], v[118:119], v[84:85], v[100:101] op_sel:[1,0,0] op_sel_hi:[1,1,1]
	v_pk_fma_f32 v[102:103], v[118:119], v[86:87], v[102:103] op_sel:[1,0,0] op_sel_hi:[1,1,1]
	v_or_b32_e32 v236, v135, v3
	global_load_dwordx4 v[68:71], v236, s[20:21]
	s_and_b32 s24, s38, 7
	s_lshl_b32 s24, s24, 9
	v_add_u32_e32 v232, s24, v228
	ds_read_b128 v[104:107], v232
	ds_read_b128 v[108:111], v232 offset:16
	ds_read_b128 v[112:115], v232 offset:32
	ds_read_b128 v[116:119], v232 offset:48
	s_add_u32 s24, s17, 2
	s_and_b32 s24, s24, 7
	s_lshl_b32 s24, s24, 9
	v_add_u32_e32 v233, s24, v228
	ds_read_b128 v[120:123], v233 offset:4096
	ds_read_b128 v[124:127], v233 offset:4112
	ds_read_b128 v[128:131], v233 offset:4128
	ds_read_b128 v[132:135], v233 offset:4144
	s_nop 1
	v_permlane32_swap_b32_e32 v88, v96
	v_permlane32_swap_b32_e32 v89, v97
	v_permlane32_swap_b32_e32 v90, v98
	v_permlane32_swap_b32_e32 v91, v99
	v_permlane32_swap_b32_e32 v92, v100
	v_permlane32_swap_b32_e32 v93, v101
	v_permlane32_swap_b32_e32 v94, v102
	v_permlane32_swap_b32_e32 v95, v103
	v_pk_add_f32 v[88:89], v[88:89], v[96:97]
	v_pk_add_f32 v[90:91], v[90:91], v[98:99]
	v_pk_add_f32 v[92:93], v[92:93], v[100:101]
	v_pk_add_f32 v[94:95], v[94:95], v[102:103]
	v_cndmask_b32_e64 v140, v88, v92, s[52:53]
	v_cndmask_b32_e64 v144, v92, v88, s[52:53]
	v_cndmask_b32_e64 v141, v89, v93, s[52:53]
	v_cndmask_b32_e64 v145, v93, v89, s[52:53]
	v_cndmask_b32_e64 v142, v90, v94, s[52:53]
	v_cndmask_b32_e64 v146, v94, v90, s[52:53]
	v_cndmask_b32_e64 v143, v91, v95, s[52:53]
	v_cndmask_b32_e64 v147, v95, v91, s[52:53]
	ds_bpermute_b32 v148, v230, v140
	ds_bpermute_b32 v149, v230, v141
	ds_bpermute_b32 v150, v230, v142
	ds_bpermute_b32 v151, v230, v143
	s_waitcnt lgkmcnt(0)
	v_pk_add_f32 v[144:145], v[144:145], v[148:149]
	v_pk_add_f32 v[146:147], v[146:147], v[150:151]
	s_nop 1
	v_add_f32_dpp v152, v144, v144 row_ror:8 row_mask:0xf bank_mask:0xf
	v_add_f32_dpp v153, v145, v145 row_ror:8 row_mask:0xf bank_mask:0xf
	v_add_f32_dpp v154, v146, v146 row_ror:8 row_mask:0xf bank_mask:0xf
	v_add_f32_dpp v155, v147, v147 row_ror:8 row_mask:0xf bank_mask:0xf
	v_cndmask_b32_e64 v156, v154, v152, s[54:55]
	v_cndmask_b32_e64 v157, v155, v153, s[54:55]
	s_waitcnt vmcnt(16)
	v_pk_add_f32 v[156:157], v[156:157], v[138:139]
	global_store_dwordx2 v231, v[156:157], s[22:23]
	s_add_u32 s17, s17, 1
	s_cmp_lt_u32 s17, 64
	s_cbranch_scc1 .Lp10_step
	s_waitcnt vmcnt(0)
	s_add_u32 s18, s18, s33
	s_cmpk_lt_u32 s18, 0x200
	s_cbranch_scc1 .Lp10_group
	v_cmp_eq_u32_e64 s[0:1], 0, v1

; __global__ void __launch_bounds__(256, 2) fwd_megakernel(Params p) {
;   __shared__ __attribute__((aligned(256))) char smem_all[SMEM_BYTES];
	.amdhsa_kernel _Z14fwd_megakernel6Params
		.amdhsa_group_segment_fixed_size 69888
		.amdhsa_private_segment_fixed_size 0
		.amdhsa_kernarg_size 712
		.amdhsa_user_sgpr_count 2
		.amdhsa_user_sgpr_dispatch_ptr 0
		.amdhsa_user_sgpr_queue_ptr 0
		.amdhsa_user_sgpr_kernarg_segment_ptr 1
		.amdhsa_user_sgpr_dispatch_id 0
		.amdhsa_user_sgpr_kernarg_preload_length 0
		.amdhsa_user_sgpr_kernarg_preload_offset 0
		.amdhsa_user_sgpr_private_segment_size 0
		.amdhsa_uses_dynamic_stack 0
		.amdhsa_enable_private_segment 0
		.amdhsa_system_sgpr_workgroup_id_x 1
		.amdhsa_system_sgpr_workgroup_id_y 0
		.amdhsa_system_sgpr_workgroup_id_z 0
		.amdhsa_system_sgpr_workgroup_info 0
		.amdhsa_system_vgpr_workitem_id 2
		.amdhsa_next_free_vgpr 254
		.amdhsa_next_free_sgpr 102
		.amdhsa_accum_offset 256
		.amdhsa_reserve_vcc 1
		.amdhsa_float_round_mode_32 0
		.amdhsa_float_round_mode_16_64 0
		.amdhsa_float_denorm_mode_32 3
		.amdhsa_float_denorm_mode_16_64 3
		.amdhsa_dx10_clamp 1
		.amdhsa_ieee_mode 1
		.amdhsa_fp16_overflow 0
		.amdhsa_tg_split 0
		.amdhsa_exception_fp_ieee_invalid_op 0
		.amdhsa_exception_fp_denorm_src 0
		.amdhsa_exception_fp_ieee_div_zero 0
		.amdhsa_exception_fp_ieee_overflow 0
		.amdhsa_exception_fp_ieee_underflow 0
		.amdhsa_exception_fp_ieee_inexact 0
		.amdhsa_exception_int_div_zero 0
	.end_amdhsa_kernel

; __global__ void __launch_bounds__(256, 2) fwd_megakernel(Params p) {
;   __shared__ __attribute__((aligned(256))) char smem_all[SMEM_BYTES];
amdhsa.kernels:
  - .agpr_count:     0
    .args:
      - .offset:         0
        .size:           456
        .value_kind:     by_value
      - .offset:         456
        .size:           4
        .value_kind:     hidden_block_count_x
      - .offset:         460
        .size:           4
        .value_kind:     hidden_block_count_y
      - .offset:         464
        .size:           4
        .value_kind:     hidden_block_count_z
      - .offset:         468
        .size:           2
        .value_kind:     hidden_group_size_x
      - .offset:         470
        .size:           2
        .value_kind:     hidden_group_size_y
      - .offset:         472
        .size:           2
        .value_kind:     hidden_group_size_z
      - .offset:         474
        .size:           2
        .value_kind:     hidden_remainder_x
      - .offset:         476
        .size:           2
        .value_kind:     hidden_remainder_y
      - .offset:         478
        .size:           2
        .value_kind:     hidden_remainder_z
      - .offset:         496
        .size:           8
        .value_kind:     hidden_global_offset_x
      - .offset:         504
        .size:           8
        .value_kind:     hidden_global_offset_y
      - .offset:         512
        .size:           8
        .value_kind:     hidden_global_offset_z
      - .offset:         520
        .size:           2
        .value_kind:     hidden_grid_dims
      - .offset:         544
        .size:           8
        .value_kind:     hidden_multigrid_sync_arg
    .group_segment_fixed_size: 69888
    .kernarg_segment_align: 8
    .kernarg_segment_size: 712
    .language:       OpenCL C
    .language_version:
      - 2
      - 0
    .max_flat_workgroup_size: 256
    .name:           _Z14fwd_megakernel6Params
    .private_segment_fixed_size: 0
    .sgpr_count:     108
    .sgpr_spill_count: 85
    .symbol:         _Z14fwd_megakernel6Params.kd
    .uniform_work_group_size: 1
    .uses_dynamic_stack: false
    .vgpr_count:     254
    .vgpr_spill_count: 0
    .wavefront_size: 64
